# scan waves run their chunk body at s_setprio 1 (reset to 0 at the end), on v192
# speedup vs baseline: 1.0019x; 1.0014x over previous
.LBB0_390:
	s_setprio 1
	s_and_b32 s3, s2, 1
	s_mul_i32 s8, s3, 0x5000
	v_add_u32_e32 v2, s8, v136
	s_mul_i32 s8, s2, 0xab
	s_bfe_u32 s8, s8, 0x70009
	s_mul_i32 s8, s8, 3
	s_sub_i32 s8, s2, s8
	s_and_b32 s8, s8, 0xff
	s_mulk_i32 s8, 0x1100
	v_add_u32_e32 v3, s8, v137
	v_lshl_add_u32 v1, s3, 12, v137
	ds_read_b128 v[176:179], v2 offset:4096
	ds_read_b128 v[180:183], v2 offset:4112
	ds_read_b128 v[200:203], v2 offset:12288
	ds_read_b128 v[204:207], v2 offset:12304
	ds_read_b64 v[216:217], v3 offset:40960
	ds_read_b128 v[184:187], v2 offset:0
	ds_read_b128 v[188:191], v2 offset:16
	ds_read_b128 v[192:195], v2 offset:8192
	ds_read_b128 v[196:199], v2 offset:8208
	s_waitcnt lgkmcnt(8)
	v_pk_mul_f32 v[164:165], v[72:73], v[176:177]
	v_pk_mul_f32 v[166:167], v[80:81], v[176:177]
	ds_read_b128 v[208:211], v2 offset:16384
	v_pk_fma_f32 v[164:165], v[74:75], v[178:179], v[164:165]
	v_pk_fma_f32 v[166:167], v[82:83], v[178:179], v[166:167]
	ds_read_b128 v[212:215], v2 offset:16400
	s_waitcnt lgkmcnt(9)
	v_pk_fma_f32 v[164:165], v[76:77], v[180:181], v[164:165]
	v_pk_fma_f32 v[166:167], v[84:85], v[180:181], v[166:167]
	ds_read_b128 v[4:7], v2 offset:4352
	v_pk_fma_f32 v[164:165], v[78:79], v[182:183], v[164:165]
	v_pk_fma_f32 v[166:167], v[86:87], v[182:183], v[166:167]
	ds_read_b128 v[8:11], v2 offset:4368
	s_waitcnt lgkmcnt(8)
	v_pk_mul_f32 v[218:219], v[216:217], v[200:201] op_sel_hi:[0,1]
	v_pk_mul_f32 v[226:227], v[216:217], v[200:201] op_sel:[1,0]
	ds_read_b128 v[40:43], v2 offset:12544
	v_pk_mul_f32 v[220:221], v[216:217], v[202:203] op_sel_hi:[0,1]
	v_pk_mul_f32 v[228:229], v[216:217], v[202:203] op_sel:[1,0]
	ds_read_b128 v[44:47], v2 offset:12560
	v_pk_mul_f32 v[222:223], v[216:217], v[204:205] op_sel_hi:[0,1]
	v_pk_mul_f32 v[230:231], v[216:217], v[204:205] op_sel:[1,0]
	ds_read_b64 v[26:27], v3 offset:41216
	v_pk_mul_f32 v[224:225], v[216:217], v[206:207] op_sel_hi:[0,1]
	v_pk_mul_f32 v[234:235], v[216:217], v[206:207] op_sel:[1,0]
	ds_read_b128 v[12:15], v2 offset:256
	v_add_f32_e32 v172, v164, v165
	v_add_f32_e32 v174, v166, v167
	ds_read_b128 v[28:31], v2 offset:272
	s_waitcnt lgkmcnt(12)
	v_pk_fma_f32 v[218:219], v[72:73], v[184:185], v[218:219]
	v_pk_fma_f32 v[226:227], v[80:81], v[184:185], v[226:227]
	ds_read_b128 v[32:35], v2 offset:8448
	v_pk_fma_f32 v[220:221], v[74:75], v[186:187], v[220:221]
	v_pk_fma_f32 v[228:229], v[82:83], v[186:187], v[228:229]
	ds_read_b128 v[36:39], v2 offset:8464
	v_add_f32_dpp v172, v172, v172 quad_perm:[1,0,3,2] row_mask:0xf bank_mask:0xf bound_ctrl:1
	v_add_f32_dpp v174, v174, v174 quad_perm:[1,0,3,2] row_mask:0xf bank_mask:0xf bound_ctrl:1
	s_waitcnt lgkmcnt(13)
	v_pk_fma_f32 v[222:223], v[76:77], v[188:189], v[222:223]
	v_pk_fma_f32 v[230:231], v[84:85], v[188:189], v[230:231]
	v_pk_fma_f32 v[224:225], v[78:79], v[190:191], v[224:225]
	v_pk_fma_f32 v[234:235], v[86:87], v[190:191], v[234:235]
	v_add_f32_dpp v172, v172, v172 quad_perm:[2,3,0,1] row_mask:0xf bank_mask:0xf bound_ctrl:1
	v_add_f32_dpp v174, v174, v174 quad_perm:[2,3,0,1] row_mask:0xf bank_mask:0xf bound_ctrl:1
	s_nop 0
	v_add_f32_dpp v172, v172, v172 row_half_mirror row_mask:0xf bank_mask:0xf bound_ctrl:1
	v_add_f32_dpp v174, v174, v174 row_half_mirror row_mask:0xf bank_mask:0xf bound_ctrl:1
	s_waitcnt lgkmcnt(12)
	v_pk_fma_f32 v[72:73], v[192:193], v[172:173], v[218:219] op_sel_hi:[1,0,1]
	v_pk_fma_f32 v[80:81], v[192:193], v[174:175], v[226:227] op_sel_hi:[1,0,1]
	v_pk_fma_f32 v[74:75], v[194:195], v[172:173], v[220:221] op_sel_hi:[1,0,1]
	v_pk_fma_f32 v[82:83], v[194:195], v[174:175], v[228:229] op_sel_hi:[1,0,1]
	s_waitcnt lgkmcnt(11)
	v_pk_fma_f32 v[76:77], v[196:197], v[172:173], v[222:223] op_sel_hi:[1,0,1]
	v_pk_fma_f32 v[84:85], v[196:197], v[174:175], v[230:231] op_sel_hi:[1,0,1]
	v_pk_fma_f32 v[78:79], v[198:199], v[172:173], v[224:225] op_sel_hi:[1,0,1]
	v_pk_fma_f32 v[86:87], v[198:199], v[174:175], v[234:235] op_sel_hi:[1,0,1]
	s_waitcnt lgkmcnt(8)
	v_pk_mul_f32 v[164:165], v[72:73], v[4:5]
	v_pk_mul_f32 v[166:167], v[80:81], v[4:5]
	ds_read_b128 v[48:51], v2 offset:16640
	v_pk_mul_f32 v[168:169], v[72:73], v[208:209]
	v_pk_mul_f32 v[170:171], v[80:81], v[208:209]
	ds_read_b128 v[52:55], v2 offset:16656
	v_pk_fma_f32 v[164:165], v[74:75], v[6:7], v[164:165]
	v_pk_fma_f32 v[166:167], v[82:83], v[6:7], v[166:167]
	ds_read_b128 v[176:179], v2 offset:4608
	v_pk_fma_f32 v[168:169], v[74:75], v[210:211], v[168:169]
	v_pk_fma_f32 v[170:171], v[82:83], v[210:211], v[170:171]
	ds_read_b128 v[180:183], v2 offset:4624
	s_waitcnt lgkmcnt(11)
	v_pk_fma_f32 v[164:165], v[76:77], v[8:9], v[164:165]
	v_pk_fma_f32 v[166:167], v[84:85], v[8:9], v[166:167]
	ds_read_b128 v[200:203], v2 offset:12800
	v_pk_fma_f32 v[168:169], v[76:77], v[212:213], v[168:169]
	v_pk_fma_f32 v[170:171], v[84:85], v[212:213], v[170:171]
	ds_read_b128 v[204:207], v2 offset:12816
	v_pk_fma_f32 v[164:165], v[78:79], v[10:11], v[164:165]
	v_pk_fma_f32 v[166:167], v[86:87], v[10:11], v[166:167]
	ds_read_b64 v[216:217], v3 offset:41472
	v_pk_fma_f32 v[168:169], v[78:79], v[214:215], v[168:169]
	v_pk_fma_f32 v[170:171], v[86:87], v[214:215], v[170:171]
	ds_read_b128 v[184:187], v2 offset:512
	s_waitcnt lgkmcnt(12)
	v_pk_mul_f32 v[218:219], v[26:27], v[40:41] op_sel_hi:[0,1]
	v_pk_mul_f32 v[226:227], v[26:27], v[40:41] op_sel:[1,0]
	ds_read_b128 v[188:191], v2 offset:528
	v_pk_mul_f32 v[220:221], v[26:27], v[42:43] op_sel_hi:[0,1]
	v_pk_mul_f32 v[228:229], v[26:27], v[42:43] op_sel:[1,0]
	ds_read_b128 v[192:195], v2 offset:8704
	v_pk_mul_f32 v[222:223], v[26:27], v[44:45] op_sel_hi:[0,1]
	v_pk_mul_f32 v[230:231], v[26:27], v[44:45] op_sel:[1,0]
	ds_read_b128 v[196:199], v2 offset:8720
	v_pk_mul_f32 v[224:225], v[26:27], v[46:47] op_sel_hi:[0,1]
	v_pk_mul_f32 v[234:235], v[26:27], v[46:47] op_sel:[1,0]
	v_add_f32_e32 v172, v164, v165
	v_add_f32_e32 v174, v166, v167
	v_add_f32_e32 v160, v168, v169
	v_add_f32_e32 v161, v170, v171
	s_waitcnt lgkmcnt(14)
	v_pk_fma_f32 v[218:219], v[72:73], v[12:13], v[218:219]
	v_pk_fma_f32 v[226:227], v[80:81], v[12:13], v[226:227]
	v_pk_fma_f32 v[220:221], v[74:75], v[14:15], v[220:221]
	v_pk_fma_f32 v[228:229], v[82:83], v[14:15], v[228:229]
	v_add_f32_dpp v172, v172, v172 quad_perm:[1,0,3,2] row_mask:0xf bank_mask:0xf bound_ctrl:1
	v_add_f32_dpp v174, v174, v174 quad_perm:[1,0,3,2] row_mask:0xf bank_mask:0xf bound_ctrl:1
	v_add_f32_dpp v160, v160, v160 quad_perm:[1,0,3,2] row_mask:0xf bank_mask:0xf bound_ctrl:1
	v_add_f32_dpp v161, v161, v161 quad_perm:[1,0,3,2] row_mask:0xf bank_mask:0xf bound_ctrl:1
	s_waitcnt lgkmcnt(13)
	v_pk_fma_f32 v[222:223], v[76:77], v[28:29], v[222:223]
	v_pk_fma_f32 v[230:231], v[84:85], v[28:29], v[230:231]
	v_pk_fma_f32 v[224:225], v[78:79], v[30:31], v[224:225]
	v_pk_fma_f32 v[234:235], v[86:87], v[30:31], v[234:235]
	v_add_f32_dpp v172, v172, v172 quad_perm:[2,3,0,1] row_mask:0xf bank_mask:0xf bound_ctrl:1
	v_add_f32_dpp v174, v174, v174 quad_perm:[2,3,0,1] row_mask:0xf bank_mask:0xf bound_ctrl:1
	v_add_f32_dpp v160, v160, v160 quad_perm:[2,3,0,1] row_mask:0xf bank_mask:0xf bound_ctrl:1
	v_add_f32_dpp v161, v161, v161 quad_perm:[2,3,0,1] row_mask:0xf bank_mask:0xf bound_ctrl:1
	v_add_f32_dpp v172, v172, v172 row_half_mirror row_mask:0xf bank_mask:0xf bound_ctrl:1
	v_add_f32_dpp v174, v174, v174 row_half_mirror row_mask:0xf bank_mask:0xf bound_ctrl:1
	v_add_f32_dpp v160, v160, v160 row_half_mirror row_mask:0xf bank_mask:0xf bound_ctrl:1
	v_add_f32_dpp v161, v161, v161 row_half_mirror row_mask:0xf bank_mask:0xf bound_ctrl:1
	s_waitcnt lgkmcnt(12)
	v_pk_fma_f32 v[72:73], v[32:33], v[172:173], v[218:219] op_sel_hi:[1,0,1]
	v_pk_fma_f32 v[80:81], v[32:33], v[174:175], v[226:227] op_sel_hi:[1,0,1]
	v_pk_fma_f32 v[74:75], v[34:35], v[172:173], v[220:221] op_sel_hi:[1,0,1]
	v_pk_fma_f32 v[82:83], v[34:35], v[174:175], v[228:229] op_sel_hi:[1,0,1]
	s_waitcnt lgkmcnt(11)
	v_pk_fma_f32 v[76:77], v[36:37], v[172:173], v[222:223] op_sel_hi:[1,0,1]
	v_pk_fma_f32 v[84:85], v[36:37], v[174:175], v[230:231] op_sel_hi:[1,0,1]
	v_pk_fma_f32 v[78:79], v[38:39], v[172:173], v[224:225] op_sel_hi:[1,0,1]
	v_pk_fma_f32 v[86:87], v[38:39], v[174:175], v[234:235] op_sel_hi:[1,0,1]
	ds_write_b64 v1, v[160:161] offset:54016
	s_waitcnt lgkmcnt(9)
	v_pk_mul_f32 v[164:165], v[72:73], v[176:177]
	v_pk_mul_f32 v[166:167], v[80:81], v[176:177]
	ds_read_b128 v[208:211], v2 offset:16896
	v_pk_mul_f32 v[168:169], v[72:73], v[48:49]
	v_pk_mul_f32 v[170:171], v[80:81], v[48:49]
	ds_read_b128 v[212:215], v2 offset:16912
	v_pk_fma_f32 v[164:165], v[74:75], v[178:179], v[164:165]
	v_pk_fma_f32 v[166:167], v[82:83], v[178:179], v[166:167]
	ds_read_b128 v[4:7], v2 offset:4864
	v_pk_fma_f32 v[168:169], v[74:75], v[50:51], v[168:169]
	v_pk_fma_f32 v[170:171], v[82:83], v[50:51], v[170:171]
	ds_read_b128 v[8:11], v2 offset:4880
	s_waitcnt lgkmcnt(12)
	v_pk_fma_f32 v[164:165], v[76:77], v[180:181], v[164:165]
	v_pk_fma_f32 v[166:167], v[84:85], v[180:181], v[166:167]
	ds_read_b128 v[40:43], v2 offset:13056
	v_pk_fma_f32 v[168:169], v[76:77], v[52:53], v[168:169]
	v_pk_fma_f32 v[170:171], v[84:85], v[52:53], v[170:171]
	ds_read_b128 v[44:47], v2 offset:13072
	v_pk_fma_f32 v[164:165], v[78:79], v[182:183], v[164:165]
	v_pk_fma_f32 v[166:167], v[86:87], v[182:183], v[166:167]
	ds_read_b64 v[26:27], v3 offset:41728
	v_pk_fma_f32 v[168:169], v[78:79], v[54:55], v[168:169]
	v_pk_fma_f32 v[170:171], v[86:87], v[54:55], v[170:171]
	ds_read_b128 v[12:15], v2 offset:768
	s_waitcnt lgkmcnt(13)
	v_pk_mul_f32 v[218:219], v[216:217], v[200:201] op_sel_hi:[0,1]
	v_pk_mul_f32 v[226:227], v[216:217], v[200:201] op_sel:[1,0]
	ds_read_b128 v[28:31], v2 offset:784
	v_pk_mul_f32 v[220:221], v[216:217], v[202:203] op_sel_hi:[0,1]
	v_pk_mul_f32 v[228:229], v[216:217], v[202:203] op_sel:[1,0]
	ds_read_b128 v[32:35], v2 offset:8960
	v_pk_mul_f32 v[222:223], v[216:217], v[204:205] op_sel_hi:[0,1]
	v_pk_mul_f32 v[230:231], v[216:217], v[204:205] op_sel:[1,0]
	ds_read_b128 v[36:39], v2 offset:8976
	v_pk_mul_f32 v[224:225], v[216:217], v[206:207] op_sel_hi:[0,1]
	v_pk_mul_f32 v[234:235], v[216:217], v[206:207] op_sel:[1,0]
	v_add_f32_e32 v172, v164, v165
	v_add_f32_e32 v174, v166, v167
	v_add_f32_e32 v160, v168, v169
	v_add_f32_e32 v161, v170, v171
	s_waitcnt lgkmcnt(15)
	v_pk_fma_f32 v[218:219], v[72:73], v[184:185], v[218:219]
	v_pk_fma_f32 v[226:227], v[80:81], v[184:185], v[226:227]
	v_pk_fma_f32 v[220:221], v[74:75], v[186:187], v[220:221]
	v_pk_fma_f32 v[228:229], v[82:83], v[186:187], v[228:229]
	v_add_f32_dpp v172, v172, v172 quad_perm:[1,0,3,2] row_mask:0xf bank_mask:0xf bound_ctrl:1
	v_add_f32_dpp v174, v174, v174 quad_perm:[1,0,3,2] row_mask:0xf bank_mask:0xf bound_ctrl:1
	v_add_f32_dpp v160, v160, v160 quad_perm:[1,0,3,2] row_mask:0xf bank_mask:0xf bound_ctrl:1
	v_add_f32_dpp v161, v161, v161 quad_perm:[1,0,3,2] row_mask:0xf bank_mask:0xf bound_ctrl:1
	s_waitcnt lgkmcnt(14)
	v_pk_fma_f32 v[222:223], v[76:77], v[188:189], v[222:223]
	v_pk_fma_f32 v[230:231], v[84:85], v[188:189], v[230:231]
	v_pk_fma_f32 v[224:225], v[78:79], v[190:191], v[224:225]
	v_pk_fma_f32 v[234:235], v[86:87], v[190:191], v[234:235]
	v_add_f32_dpp v172, v172, v172 quad_perm:[2,3,0,1] row_mask:0xf bank_mask:0xf bound_ctrl:1
	v_add_f32_dpp v174, v174, v174 quad_perm:[2,3,0,1] row_mask:0xf bank_mask:0xf bound_ctrl:1
	v_add_f32_dpp v160, v160, v160 quad_perm:[2,3,0,1] row_mask:0xf bank_mask:0xf bound_ctrl:1
	v_add_f32_dpp v161, v161, v161 quad_perm:[2,3,0,1] row_mask:0xf bank_mask:0xf bound_ctrl:1
	v_add_f32_dpp v172, v172, v172 row_half_mirror row_mask:0xf bank_mask:0xf bound_ctrl:1
	v_add_f32_dpp v174, v174, v174 row_half_mirror row_mask:0xf bank_mask:0xf bound_ctrl:1
	v_add_f32_dpp v160, v160, v160 row_half_mirror row_mask:0xf bank_mask:0xf bound_ctrl:1
	v_add_f32_dpp v161, v161, v161 row_half_mirror row_mask:0xf bank_mask:0xf bound_ctrl:1
	s_waitcnt lgkmcnt(13)
	v_pk_fma_f32 v[72:73], v[192:193], v[172:173], v[218:219] op_sel_hi:[1,0,1]
	v_pk_fma_f32 v[80:81], v[192:193], v[174:175], v[226:227] op_sel_hi:[1,0,1]
	v_pk_fma_f32 v[74:75], v[194:195], v[172:173], v[220:221] op_sel_hi:[1,0,1]
	v_pk_fma_f32 v[82:83], v[194:195], v[174:175], v[228:229] op_sel_hi:[1,0,1]
	s_waitcnt lgkmcnt(12)
	v_pk_fma_f32 v[76:77], v[196:197], v[172:173], v[222:223] op_sel_hi:[1,0,1]
	v_pk_fma_f32 v[84:85], v[196:197], v[174:175], v[230:231] op_sel_hi:[1,0,1]
	v_pk_fma_f32 v[78:79], v[198:199], v[172:173], v[224:225] op_sel_hi:[1,0,1]
	v_pk_fma_f32 v[86:87], v[198:199], v[174:175], v[234:235] op_sel_hi:[1,0,1]
	ds_write_b64 v1, v[160:161] offset:54272
	s_waitcnt lgkmcnt(9)
	v_pk_mul_f32 v[164:165], v[72:73], v[4:5]
	v_pk_mul_f32 v[166:167], v[80:81], v[4:5]
	ds_read_b128 v[48:51], v2 offset:17152
	v_pk_mul_f32 v[168:169], v[72:73], v[208:209]
	v_pk_mul_f32 v[170:171], v[80:81], v[208:209]
	ds_read_b128 v[52:55], v2 offset:17168
	v_pk_fma_f32 v[164:165], v[74:75], v[6:7], v[164:165]
	v_pk_fma_f32 v[166:167], v[82:83], v[6:7], v[166:167]
	ds_read_b128 v[176:179], v2 offset:5120
	v_pk_fma_f32 v[168:169], v[74:75], v[210:211], v[168:169]
	v_pk_fma_f32 v[170:171], v[82:83], v[210:211], v[170:171]
	ds_read_b128 v[180:183], v2 offset:5136
	s_waitcnt lgkmcnt(12)
	v_pk_fma_f32 v[164:165], v[76:77], v[8:9], v[164:165]
	v_pk_fma_f32 v[166:167], v[84:85], v[8:9], v[166:167]
	ds_read_b128 v[200:203], v2 offset:13312
	v_pk_fma_f32 v[168:169], v[76:77], v[212:213], v[168:169]
	v_pk_fma_f32 v[170:171], v[84:85], v[212:213], v[170:171]
	ds_read_b128 v[204:207], v2 offset:13328
	v_pk_fma_f32 v[164:165], v[78:79], v[10:11], v[164:165]
	v_pk_fma_f32 v[166:167], v[86:87], v[10:11], v[166:167]
	ds_read_b64 v[216:217], v3 offset:41984
	v_pk_fma_f32 v[168:169], v[78:79], v[214:215], v[168:169]
	v_pk_fma_f32 v[170:171], v[86:87], v[214:215], v[170:171]
	ds_read_b128 v[184:187], v2 offset:1024
	s_waitcnt lgkmcnt(13)
	v_pk_mul_f32 v[218:219], v[26:27], v[40:41] op_sel_hi:[0,1]
	v_pk_mul_f32 v[226:227], v[26:27], v[40:41] op_sel:[1,0]
	ds_read_b128 v[188:191], v2 offset:1040
	v_pk_mul_f32 v[220:221], v[26:27], v[42:43] op_sel_hi:[0,1]
	v_pk_mul_f32 v[228:229], v[26:27], v[42:43] op_sel:[1,0]
	ds_read_b128 v[192:195], v2 offset:9216
	v_pk_mul_f32 v[222:223], v[26:27], v[44:45] op_sel_hi:[0,1]
	v_pk_mul_f32 v[230:231], v[26:27], v[44:45] op_sel:[1,0]
	ds_read_b128 v[196:199], v2 offset:9232
	v_pk_mul_f32 v[224:225], v[26:27], v[46:47] op_sel_hi:[0,1]
	v_pk_mul_f32 v[234:235], v[26:27], v[46:47] op_sel:[1,0]
	v_add_f32_e32 v172, v164, v165
	v_add_f32_e32 v174, v166, v167
	v_add_f32_e32 v160, v168, v169
	v_add_f32_e32 v161, v170, v171
	s_waitcnt lgkmcnt(15)
	v_pk_fma_f32 v[218:219], v[72:73], v[12:13], v[218:219]
	v_pk_fma_f32 v[226:227], v[80:81], v[12:13], v[226:227]
	v_pk_fma_f32 v[220:221], v[74:75], v[14:15], v[220:221]
	v_pk_fma_f32 v[228:229], v[82:83], v[14:15], v[228:229]
	v_add_f32_dpp v172, v172, v172 quad_perm:[1,0,3,2] row_mask:0xf bank_mask:0xf bound_ctrl:1
	v_add_f32_dpp v174, v174, v174 quad_perm:[1,0,3,2] row_mask:0xf bank_mask:0xf bound_ctrl:1
	v_add_f32_dpp v160, v160, v160 quad_perm:[1,0,3,2] row_mask:0xf bank_mask:0xf bound_ctrl:1
	v_add_f32_dpp v161, v161, v161 quad_perm:[1,0,3,2] row_mask:0xf bank_mask:0xf bound_ctrl:1
	s_waitcnt lgkmcnt(14)
	v_pk_fma_f32 v[222:223], v[76:77], v[28:29], v[222:223]
	v_pk_fma_f32 v[230:231], v[84:85], v[28:29], v[230:231]
	v_pk_fma_f32 v[224:225], v[78:79], v[30:31], v[224:225]
	v_pk_fma_f32 v[234:235], v[86:87], v[30:31], v[234:235]
	v_add_f32_dpp v172, v172, v172 quad_perm:[2,3,0,1] row_mask:0xf bank_mask:0xf bound_ctrl:1
	v_add_f32_dpp v174, v174, v174 quad_perm:[2,3,0,1] row_mask:0xf bank_mask:0xf bound_ctrl:1
	v_add_f32_dpp v160, v160, v160 quad_perm:[2,3,0,1] row_mask:0xf bank_mask:0xf bound_ctrl:1
	v_add_f32_dpp v161, v161, v161 quad_perm:[2,3,0,1] row_mask:0xf bank_mask:0xf bound_ctrl:1
	v_add_f32_dpp v172, v172, v172 row_half_mirror row_mask:0xf bank_mask:0xf bound_ctrl:1
	v_add_f32_dpp v174, v174, v174 row_half_mirror row_mask:0xf bank_mask:0xf bound_ctrl:1
	v_add_f32_dpp v160, v160, v160 row_half_mirror row_mask:0xf bank_mask:0xf bound_ctrl:1
	v_add_f32_dpp v161, v161, v161 row_half_mirror row_mask:0xf bank_mask:0xf bound_ctrl:1
	s_waitcnt lgkmcnt(13)
	v_pk_fma_f32 v[72:73], v[32:33], v[172:173], v[218:219] op_sel_hi:[1,0,1]
	v_pk_fma_f32 v[80:81], v[32:33], v[174:175], v[226:227] op_sel_hi:[1,0,1]
	v_pk_fma_f32 v[74:75], v[34:35], v[172:173], v[220:221] op_sel_hi:[1,0,1]
	v_pk_fma_f32 v[82:83], v[34:35], v[174:175], v[228:229] op_sel_hi:[1,0,1]
	s_waitcnt lgkmcnt(12)
	v_pk_fma_f32 v[76:77], v[36:37], v[172:173], v[222:223] op_sel_hi:[1,0,1]
	v_pk_fma_f32 v[84:85], v[36:37], v[174:175], v[230:231] op_sel_hi:[1,0,1]
	v_pk_fma_f32 v[78:79], v[38:39], v[172:173], v[224:225] op_sel_hi:[1,0,1]
	v_pk_fma_f32 v[86:87], v[38:39], v[174:175], v[234:235] op_sel_hi:[1,0,1]
	ds_write_b64 v1, v[160:161] offset:54528
	s_waitcnt lgkmcnt(9)
	v_pk_mul_f32 v[164:165], v[72:73], v[176:177]
	v_pk_mul_f32 v[166:167], v[80:81], v[176:177]
	ds_read_b128 v[208:211], v2 offset:17408
	v_pk_mul_f32 v[168:169], v[72:73], v[48:49]
	v_pk_mul_f32 v[170:171], v[80:81], v[48:49]
	ds_read_b128 v[212:215], v2 offset:17424
	v_pk_fma_f32 v[164:165], v[74:75], v[178:179], v[164:165]
	v_pk_fma_f32 v[166:167], v[82:83], v[178:179], v[166:167]
	ds_read_b128 v[4:7], v2 offset:5376
	v_pk_fma_f32 v[168:169], v[74:75], v[50:51], v[168:169]
	v_pk_fma_f32 v[170:171], v[82:83], v[50:51], v[170:171]
	ds_read_b128 v[8:11], v2 offset:5392
	s_waitcnt lgkmcnt(12)
	v_pk_fma_f32 v[164:165], v[76:77], v[180:181], v[164:165]
	v_pk_fma_f32 v[166:167], v[84:85], v[180:181], v[166:167]
	ds_read_b128 v[40:43], v2 offset:13568
	v_pk_fma_f32 v[168:169], v[76:77], v[52:53], v[168:169]
	v_pk_fma_f32 v[170:171], v[84:85], v[52:53], v[170:171]
	ds_read_b128 v[44:47], v2 offset:13584
	v_pk_fma_f32 v[164:165], v[78:79], v[182:183], v[164:165]
	v_pk_fma_f32 v[166:167], v[86:87], v[182:183], v[166:167]
	ds_read_b64 v[26:27], v3 offset:42240
	v_pk_fma_f32 v[168:169], v[78:79], v[54:55], v[168:169]
	v_pk_fma_f32 v[170:171], v[86:87], v[54:55], v[170:171]
	ds_read_b128 v[12:15], v2 offset:1280
	s_waitcnt lgkmcnt(13)
	v_pk_mul_f32 v[218:219], v[216:217], v[200:201] op_sel_hi:[0,1]
	v_pk_mul_f32 v[226:227], v[216:217], v[200:201] op_sel:[1,0]
	ds_read_b128 v[28:31], v2 offset:1296
	v_pk_mul_f32 v[220:221], v[216:217], v[202:203] op_sel_hi:[0,1]
	v_pk_mul_f32 v[228:229], v[216:217], v[202:203] op_sel:[1,0]
	ds_read_b128 v[32:35], v2 offset:9472
	v_pk_mul_f32 v[222:223], v[216:217], v[204:205] op_sel_hi:[0,1]
	v_pk_mul_f32 v[230:231], v[216:217], v[204:205] op_sel:[1,0]
	ds_read_b128 v[36:39], v2 offset:9488
	v_pk_mul_f32 v[224:225], v[216:217], v[206:207] op_sel_hi:[0,1]
	v_pk_mul_f32 v[234:235], v[216:217], v[206:207] op_sel:[1,0]
	v_add_f32_e32 v172, v164, v165
	v_add_f32_e32 v174, v166, v167
	v_add_f32_e32 v160, v168, v169
	v_add_f32_e32 v161, v170, v171
	s_waitcnt lgkmcnt(15)
	v_pk_fma_f32 v[218:219], v[72:73], v[184:185], v[218:219]
	v_pk_fma_f32 v[226:227], v[80:81], v[184:185], v[226:227]
	v_pk_fma_f32 v[220:221], v[74:75], v[186:187], v[220:221]
	v_pk_fma_f32 v[228:229], v[82:83], v[186:187], v[228:229]
	v_add_f32_dpp v172, v172, v172 quad_perm:[1,0,3,2] row_mask:0xf bank_mask:0xf bound_ctrl:1
	v_add_f32_dpp v174, v174, v174 quad_perm:[1,0,3,2] row_mask:0xf bank_mask:0xf bound_ctrl:1
	v_add_f32_dpp v160, v160, v160 quad_perm:[1,0,3,2] row_mask:0xf bank_mask:0xf bound_ctrl:1
	v_add_f32_dpp v161, v161, v161 quad_perm:[1,0,3,2] row_mask:0xf bank_mask:0xf bound_ctrl:1
	s_waitcnt lgkmcnt(14)
	v_pk_fma_f32 v[222:223], v[76:77], v[188:189], v[222:223]
	v_pk_fma_f32 v[230:231], v[84:85], v[188:189], v[230:231]
	v_pk_fma_f32 v[224:225], v[78:79], v[190:191], v[224:225]
	v_pk_fma_f32 v[234:235], v[86:87], v[190:191], v[234:235]
	v_add_f32_dpp v172, v172, v172 quad_perm:[2,3,0,1] row_mask:0xf bank_mask:0xf bound_ctrl:1
	v_add_f32_dpp v174, v174, v174 quad_perm:[2,3,0,1] row_mask:0xf bank_mask:0xf bound_ctrl:1
	v_add_f32_dpp v160, v160, v160 quad_perm:[2,3,0,1] row_mask:0xf bank_mask:0xf bound_ctrl:1
	v_add_f32_dpp v161, v161, v161 quad_perm:[2,3,0,1] row_mask:0xf bank_mask:0xf bound_ctrl:1
	v_add_f32_dpp v172, v172, v172 row_half_mirror row_mask:0xf bank_mask:0xf bound_ctrl:1
	v_add_f32_dpp v174, v174, v174 row_half_mirror row_mask:0xf bank_mask:0xf bound_ctrl:1
	v_add_f32_dpp v160, v160, v160 row_half_mirror row_mask:0xf bank_mask:0xf bound_ctrl:1
	v_add_f32_dpp v161, v161, v161 row_half_mirror row_mask:0xf bank_mask:0xf bound_ctrl:1
	s_waitcnt lgkmcnt(13)
	v_pk_fma_f32 v[72:73], v[192:193], v[172:173], v[218:219] op_sel_hi:[1,0,1]
	v_pk_fma_f32 v[80:81], v[192:193], v[174:175], v[226:227] op_sel_hi:[1,0,1]
	v_pk_fma_f32 v[74:75], v[194:195], v[172:173], v[220:221] op_sel_hi:[1,0,1]
	v_pk_fma_f32 v[82:83], v[194:195], v[174:175], v[228:229] op_sel_hi:[1,0,1]
	s_waitcnt lgkmcnt(12)
	v_pk_fma_f32 v[76:77], v[196:197], v[172:173], v[222:223] op_sel_hi:[1,0,1]
	v_pk_fma_f32 v[84:85], v[196:197], v[174:175], v[230:231] op_sel_hi:[1,0,1]
	v_pk_fma_f32 v[78:79], v[198:199], v[172:173], v[224:225] op_sel_hi:[1,0,1]
	v_pk_fma_f32 v[86:87], v[198:199], v[174:175], v[234:235] op_sel_hi:[1,0,1]
	ds_write_b64 v1, v[160:161] offset:54784
	s_waitcnt lgkmcnt(9)
	v_pk_mul_f32 v[164:165], v[72:73], v[4:5]
	v_pk_mul_f32 v[166:167], v[80:81], v[4:5]
	ds_read_b128 v[48:51], v2 offset:17664
	v_pk_mul_f32 v[168:169], v[72:73], v[208:209]
	v_pk_mul_f32 v[170:171], v[80:81], v[208:209]
	ds_read_b128 v[52:55], v2 offset:17680
	v_pk_fma_f32 v[164:165], v[74:75], v[6:7], v[164:165]
	v_pk_fma_f32 v[166:167], v[82:83], v[6:7], v[166:167]
	ds_read_b128 v[176:179], v2 offset:5632
	v_pk_fma_f32 v[168:169], v[74:75], v[210:211], v[168:169]
	v_pk_fma_f32 v[170:171], v[82:83], v[210:211], v[170:171]
	ds_read_b128 v[180:183], v2 offset:5648
	s_waitcnt lgkmcnt(12)
	v_pk_fma_f32 v[164:165], v[76:77], v[8:9], v[164:165]
	v_pk_fma_f32 v[166:167], v[84:85], v[8:9], v[166:167]
	ds_read_b128 v[200:203], v2 offset:13824
	v_pk_fma_f32 v[168:169], v[76:77], v[212:213], v[168:169]
	v_pk_fma_f32 v[170:171], v[84:85], v[212:213], v[170:171]
	ds_read_b128 v[204:207], v2 offset:13840
	v_pk_fma_f32 v[164:165], v[78:79], v[10:11], v[164:165]
	v_pk_fma_f32 v[166:167], v[86:87], v[10:11], v[166:167]
	ds_read_b64 v[216:217], v3 offset:42496
	v_pk_fma_f32 v[168:169], v[78:79], v[214:215], v[168:169]
	v_pk_fma_f32 v[170:171], v[86:87], v[214:215], v[170:171]
	ds_read_b128 v[184:187], v2 offset:1536
	s_waitcnt lgkmcnt(13)
	v_pk_mul_f32 v[218:219], v[26:27], v[40:41] op_sel_hi:[0,1]
	v_pk_mul_f32 v[226:227], v[26:27], v[40:41] op_sel:[1,0]
	ds_read_b128 v[188:191], v2 offset:1552
	v_pk_mul_f32 v[220:221], v[26:27], v[42:43] op_sel_hi:[0,1]
	v_pk_mul_f32 v[228:229], v[26:27], v[42:43] op_sel:[1,0]
	ds_read_b128 v[192:195], v2 offset:9728
	v_pk_mul_f32 v[222:223], v[26:27], v[44:45] op_sel_hi:[0,1]
	v_pk_mul_f32 v[230:231], v[26:27], v[44:45] op_sel:[1,0]
	ds_read_b128 v[196:199], v2 offset:9744
	v_pk_mul_f32 v[224:225], v[26:27], v[46:47] op_sel_hi:[0,1]
	v_pk_mul_f32 v[234:235], v[26:27], v[46:47] op_sel:[1,0]
	v_add_f32_e32 v172, v164, v165
	v_add_f32_e32 v174, v166, v167
	v_add_f32_e32 v160, v168, v169
	v_add_f32_e32 v161, v170, v171
	s_waitcnt lgkmcnt(15)
	v_pk_fma_f32 v[218:219], v[72:73], v[12:13], v[218:219]
	v_pk_fma_f32 v[226:227], v[80:81], v[12:13], v[226:227]
	v_pk_fma_f32 v[220:221], v[74:75], v[14:15], v[220:221]
	v_pk_fma_f32 v[228:229], v[82:83], v[14:15], v[228:229]
	v_add_f32_dpp v172, v172, v172 quad_perm:[1,0,3,2] row_mask:0xf bank_mask:0xf bound_ctrl:1
	v_add_f32_dpp v174, v174, v174 quad_perm:[1,0,3,2] row_mask:0xf bank_mask:0xf bound_ctrl:1
	v_add_f32_dpp v160, v160, v160 quad_perm:[1,0,3,2] row_mask:0xf bank_mask:0xf bound_ctrl:1
	v_add_f32_dpp v161, v161, v161 quad_perm:[1,0,3,2] row_mask:0xf bank_mask:0xf bound_ctrl:1
	s_waitcnt lgkmcnt(14)
	v_pk_fma_f32 v[222:223], v[76:77], v[28:29], v[222:223]
	v_pk_fma_f32 v[230:231], v[84:85], v[28:29], v[230:231]
	v_pk_fma_f32 v[224:225], v[78:79], v[30:31], v[224:225]
	v_pk_fma_f32 v[234:235], v[86:87], v[30:31], v[234:235]
	v_add_f32_dpp v172, v172, v172 quad_perm:[2,3,0,1] row_mask:0xf bank_mask:0xf bound_ctrl:1
	v_add_f32_dpp v174, v174, v174 quad_perm:[2,3,0,1] row_mask:0xf bank_mask:0xf bound_ctrl:1
	v_add_f32_dpp v160, v160, v160 quad_perm:[2,3,0,1] row_mask:0xf bank_mask:0xf bound_ctrl:1
	v_add_f32_dpp v161, v161, v161 quad_perm:[2,3,0,1] row_mask:0xf bank_mask:0xf bound_ctrl:1
	v_add_f32_dpp v172, v172, v172 row_half_mirror row_mask:0xf bank_mask:0xf bound_ctrl:1
	v_add_f32_dpp v174, v174, v174 row_half_mirror row_mask:0xf bank_mask:0xf bound_ctrl:1
	v_add_f32_dpp v160, v160, v160 row_half_mirror row_mask:0xf bank_mask:0xf bound_ctrl:1
	v_add_f32_dpp v161, v161, v161 row_half_mirror row_mask:0xf bank_mask:0xf bound_ctrl:1
	s_waitcnt lgkmcnt(13)
	v_pk_fma_f32 v[72:73], v[32:33], v[172:173], v[218:219] op_sel_hi:[1,0,1]
	v_pk_fma_f32 v[80:81], v[32:33], v[174:175], v[226:227] op_sel_hi:[1,0,1]
	v_pk_fma_f32 v[74:75], v[34:35], v[172:173], v[220:221] op_sel_hi:[1,0,1]
	v_pk_fma_f32 v[82:83], v[34:35], v[174:175], v[228:229] op_sel_hi:[1,0,1]
	s_waitcnt lgkmcnt(12)
	v_pk_fma_f32 v[76:77], v[36:37], v[172:173], v[222:223] op_sel_hi:[1,0,1]
	v_pk_fma_f32 v[84:85], v[36:37], v[174:175], v[230:231] op_sel_hi:[1,0,1]
	v_pk_fma_f32 v[78:79], v[38:39], v[172:173], v[224:225] op_sel_hi:[1,0,1]
	v_pk_fma_f32 v[86:87], v[38:39], v[174:175], v[234:235] op_sel_hi:[1,0,1]
	ds_write_b64 v1, v[160:161] offset:55040
	s_waitcnt lgkmcnt(9)
	v_pk_mul_f32 v[164:165], v[72:73], v[176:177]
	v_pk_mul_f32 v[166:167], v[80:81], v[176:177]
	ds_read_b128 v[208:211], v2 offset:17920
	v_pk_mul_f32 v[168:169], v[72:73], v[48:49]
	v_pk_mul_f32 v[170:171], v[80:81], v[48:49]
	ds_read_b128 v[212:215], v2 offset:17936
	v_pk_fma_f32 v[164:165], v[74:75], v[178:179], v[164:165]
	v_pk_fma_f32 v[166:167], v[82:83], v[178:179], v[166:167]
	ds_read_b128 v[4:7], v2 offset:5888
	v_pk_fma_f32 v[168:169], v[74:75], v[50:51], v[168:169]
	v_pk_fma_f32 v[170:171], v[82:83], v[50:51], v[170:171]
	ds_read_b128 v[8:11], v2 offset:5904
	s_waitcnt lgkmcnt(12)
	v_pk_fma_f32 v[164:165], v[76:77], v[180:181], v[164:165]
	v_pk_fma_f32 v[166:167], v[84:85], v[180:181], v[166:167]
	ds_read_b128 v[40:43], v2 offset:14080
	v_pk_fma_f32 v[168:169], v[76:77], v[52:53], v[168:169]
	v_pk_fma_f32 v[170:171], v[84:85], v[52:53], v[170:171]
	ds_read_b128 v[44:47], v2 offset:14096
	v_pk_fma_f32 v[164:165], v[78:79], v[182:183], v[164:165]
	v_pk_fma_f32 v[166:167], v[86:87], v[182:183], v[166:167]
	ds_read_b64 v[26:27], v3 offset:42752
	v_pk_fma_f32 v[168:169], v[78:79], v[54:55], v[168:169]
	v_pk_fma_f32 v[170:171], v[86:87], v[54:55], v[170:171]
	ds_read_b128 v[12:15], v2 offset:1792
	s_waitcnt lgkmcnt(13)
	v_pk_mul_f32 v[218:219], v[216:217], v[200:201] op_sel_hi:[0,1]
	v_pk_mul_f32 v[226:227], v[216:217], v[200:201] op_sel:[1,0]
	ds_read_b128 v[28:31], v2 offset:1808
	v_pk_mul_f32 v[220:221], v[216:217], v[202:203] op_sel_hi:[0,1]
	v_pk_mul_f32 v[228:229], v[216:217], v[202:203] op_sel:[1,0]
	ds_read_b128 v[32:35], v2 offset:9984
	v_pk_mul_f32 v[222:223], v[216:217], v[204:205] op_sel_hi:[0,1]
	v_pk_mul_f32 v[230:231], v[216:217], v[204:205] op_sel:[1,0]
	ds_read_b128 v[36:39], v2 offset:10000
	v_pk_mul_f32 v[224:225], v[216:217], v[206:207] op_sel_hi:[0,1]
	v_pk_mul_f32 v[234:235], v[216:217], v[206:207] op_sel:[1,0]
	v_add_f32_e32 v172, v164, v165
	v_add_f32_e32 v174, v166, v167
	v_add_f32_e32 v160, v168, v169
	v_add_f32_e32 v161, v170, v171
	s_waitcnt lgkmcnt(15)
	v_pk_fma_f32 v[218:219], v[72:73], v[184:185], v[218:219]
	v_pk_fma_f32 v[226:227], v[80:81], v[184:185], v[226:227]
	v_pk_fma_f32 v[220:221], v[74:75], v[186:187], v[220:221]
	v_pk_fma_f32 v[228:229], v[82:83], v[186:187], v[228:229]
	v_add_f32_dpp v172, v172, v172 quad_perm:[1,0,3,2] row_mask:0xf bank_mask:0xf bound_ctrl:1
	v_add_f32_dpp v174, v174, v174 quad_perm:[1,0,3,2] row_mask:0xf bank_mask:0xf bound_ctrl:1
	v_add_f32_dpp v160, v160, v160 quad_perm:[1,0,3,2] row_mask:0xf bank_mask:0xf bound_ctrl:1
	v_add_f32_dpp v161, v161, v161 quad_perm:[1,0,3,2] row_mask:0xf bank_mask:0xf bound_ctrl:1
	s_waitcnt lgkmcnt(14)
	v_pk_fma_f32 v[222:223], v[76:77], v[188:189], v[222:223]
	v_pk_fma_f32 v[230:231], v[84:85], v[188:189], v[230:231]
	v_pk_fma_f32 v[224:225], v[78:79], v[190:191], v[224:225]
	v_pk_fma_f32 v[234:235], v[86:87], v[190:191], v[234:235]
	v_add_f32_dpp v172, v172, v172 quad_perm:[2,3,0,1] row_mask:0xf bank_mask:0xf bound_ctrl:1
	v_add_f32_dpp v174, v174, v174 quad_perm:[2,3,0,1] row_mask:0xf bank_mask:0xf bound_ctrl:1
	v_add_f32_dpp v160, v160, v160 quad_perm:[2,3,0,1] row_mask:0xf bank_mask:0xf bound_ctrl:1
	v_add_f32_dpp v161, v161, v161 quad_perm:[2,3,0,1] row_mask:0xf bank_mask:0xf bound_ctrl:1
	v_add_f32_dpp v172, v172, v172 row_half_mirror row_mask:0xf bank_mask:0xf bound_ctrl:1
	v_add_f32_dpp v174, v174, v174 row_half_mirror row_mask:0xf bank_mask:0xf bound_ctrl:1
	v_add_f32_dpp v160, v160, v160 row_half_mirror row_mask:0xf bank_mask:0xf bound_ctrl:1
	v_add_f32_dpp v161, v161, v161 row_half_mirror row_mask:0xf bank_mask:0xf bound_ctrl:1
	s_waitcnt lgkmcnt(13)
	v_pk_fma_f32 v[72:73], v[192:193], v[172:173], v[218:219] op_sel_hi:[1,0,1]
	v_pk_fma_f32 v[80:81], v[192:193], v[174:175], v[226:227] op_sel_hi:[1,0,1]
	v_pk_fma_f32 v[74:75], v[194:195], v[172:173], v[220:221] op_sel_hi:[1,0,1]
	v_pk_fma_f32 v[82:83], v[194:195], v[174:175], v[228:229] op_sel_hi:[1,0,1]
	s_waitcnt lgkmcnt(12)
	v_pk_fma_f32 v[76:77], v[196:197], v[172:173], v[222:223] op_sel_hi:[1,0,1]
	v_pk_fma_f32 v[84:85], v[196:197], v[174:175], v[230:231] op_sel_hi:[1,0,1]
	v_pk_fma_f32 v[78:79], v[198:199], v[172:173], v[224:225] op_sel_hi:[1,0,1]
	v_pk_fma_f32 v[86:87], v[198:199], v[174:175], v[234:235] op_sel_hi:[1,0,1]
	ds_write_b64 v1, v[160:161] offset:55296
	s_waitcnt lgkmcnt(9)
	v_pk_mul_f32 v[164:165], v[72:73], v[4:5]
	v_pk_mul_f32 v[166:167], v[80:81], v[4:5]
	ds_read_b128 v[48:51], v2 offset:18176
	v_pk_mul_f32 v[168:169], v[72:73], v[208:209]
	v_pk_mul_f32 v[170:171], v[80:81], v[208:209]
	ds_read_b128 v[52:55], v2 offset:18192
	v_pk_fma_f32 v[164:165], v[74:75], v[6:7], v[164:165]
	v_pk_fma_f32 v[166:167], v[82:83], v[6:7], v[166:167]
	ds_read_b128 v[176:179], v2 offset:6144
	v_pk_fma_f32 v[168:169], v[74:75], v[210:211], v[168:169]
	v_pk_fma_f32 v[170:171], v[82:83], v[210:211], v[170:171]
	ds_read_b128 v[180:183], v2 offset:6160
	s_waitcnt lgkmcnt(12)
	v_pk_fma_f32 v[164:165], v[76:77], v[8:9], v[164:165]
	v_pk_fma_f32 v[166:167], v[84:85], v[8:9], v[166:167]
	ds_read_b128 v[200:203], v2 offset:14336
	v_pk_fma_f32 v[168:169], v[76:77], v[212:213], v[168:169]
	v_pk_fma_f32 v[170:171], v[84:85], v[212:213], v[170:171]
	ds_read_b128 v[204:207], v2 offset:14352
	v_pk_fma_f32 v[164:165], v[78:79], v[10:11], v[164:165]
	v_pk_fma_f32 v[166:167], v[86:87], v[10:11], v[166:167]
	ds_read_b64 v[216:217], v3 offset:43008
	v_pk_fma_f32 v[168:169], v[78:79], v[214:215], v[168:169]
	v_pk_fma_f32 v[170:171], v[86:87], v[214:215], v[170:171]
	ds_read_b128 v[184:187], v2 offset:2048
	s_waitcnt lgkmcnt(13)
	v_pk_mul_f32 v[218:219], v[26:27], v[40:41] op_sel_hi:[0,1]
	v_pk_mul_f32 v[226:227], v[26:27], v[40:41] op_sel:[1,0]
	ds_read_b128 v[188:191], v2 offset:2064
	v_pk_mul_f32 v[220:221], v[26:27], v[42:43] op_sel_hi:[0,1]
	v_pk_mul_f32 v[228:229], v[26:27], v[42:43] op_sel:[1,0]
	ds_read_b128 v[192:195], v2 offset:10240
	v_pk_mul_f32 v[222:223], v[26:27], v[44:45] op_sel_hi:[0,1]
	v_pk_mul_f32 v[230:231], v[26:27], v[44:45] op_sel:[1,0]
	ds_read_b128 v[196:199], v2 offset:10256
	v_pk_mul_f32 v[224:225], v[26:27], v[46:47] op_sel_hi:[0,1]
	v_pk_mul_f32 v[234:235], v[26:27], v[46:47] op_sel:[1,0]
	v_add_f32_e32 v172, v164, v165
	v_add_f32_e32 v174, v166, v167
	v_add_f32_e32 v160, v168, v169
	v_add_f32_e32 v161, v170, v171
	s_waitcnt lgkmcnt(15)
	v_pk_fma_f32 v[218:219], v[72:73], v[12:13], v[218:219]
	v_pk_fma_f32 v[226:227], v[80:81], v[12:13], v[226:227]
	v_pk_fma_f32 v[220:221], v[74:75], v[14:15], v[220:221]
	v_pk_fma_f32 v[228:229], v[82:83], v[14:15], v[228:229]
	v_add_f32_dpp v172, v172, v172 quad_perm:[1,0,3,2] row_mask:0xf bank_mask:0xf bound_ctrl:1
	v_add_f32_dpp v174, v174, v174 quad_perm:[1,0,3,2] row_mask:0xf bank_mask:0xf bound_ctrl:1
	v_add_f32_dpp v160, v160, v160 quad_perm:[1,0,3,2] row_mask:0xf bank_mask:0xf bound_ctrl:1
	v_add_f32_dpp v161, v161, v161 quad_perm:[1,0,3,2] row_mask:0xf bank_mask:0xf bound_ctrl:1
	s_waitcnt lgkmcnt(14)
	v_pk_fma_f32 v[222:223], v[76:77], v[28:29], v[222:223]
	v_pk_fma_f32 v[230:231], v[84:85], v[28:29], v[230:231]
	v_pk_fma_f32 v[224:225], v[78:79], v[30:31], v[224:225]
	v_pk_fma_f32 v[234:235], v[86:87], v[30:31], v[234:235]
	v_add_f32_dpp v172, v172, v172 quad_perm:[2,3,0,1] row_mask:0xf bank_mask:0xf bound_ctrl:1
	v_add_f32_dpp v174, v174, v174 quad_perm:[2,3,0,1] row_mask:0xf bank_mask:0xf bound_ctrl:1
	v_add_f32_dpp v160, v160, v160 quad_perm:[2,3,0,1] row_mask:0xf bank_mask:0xf bound_ctrl:1
	v_add_f32_dpp v161, v161, v161 quad_perm:[2,3,0,1] row_mask:0xf bank_mask:0xf bound_ctrl:1
	v_add_f32_dpp v172, v172, v172 row_half_mirror row_mask:0xf bank_mask:0xf bound_ctrl:1
	v_add_f32_dpp v174, v174, v174 row_half_mirror row_mask:0xf bank_mask:0xf bound_ctrl:1
	v_add_f32_dpp v160, v160, v160 row_half_mirror row_mask:0xf bank_mask:0xf bound_ctrl:1
	v_add_f32_dpp v161, v161, v161 row_half_mirror row_mask:0xf bank_mask:0xf bound_ctrl:1
	s_waitcnt lgkmcnt(13)
	v_pk_fma_f32 v[72:73], v[32:33], v[172:173], v[218:219] op_sel_hi:[1,0,1]
	v_pk_fma_f32 v[80:81], v[32:33], v[174:175], v[226:227] op_sel_hi:[1,0,1]
	v_pk_fma_f32 v[74:75], v[34:35], v[172:173], v[220:221] op_sel_hi:[1,0,1]
	v_pk_fma_f32 v[82:83], v[34:35], v[174:175], v[228:229] op_sel_hi:[1,0,1]
	s_waitcnt lgkmcnt(12)
	v_pk_fma_f32 v[76:77], v[36:37], v[172:173], v[222:223] op_sel_hi:[1,0,1]
	v_pk_fma_f32 v[84:85], v[36:37], v[174:175], v[230:231] op_sel_hi:[1,0,1]
	v_pk_fma_f32 v[78:79], v[38:39], v[172:173], v[224:225] op_sel_hi:[1,0,1]
	v_pk_fma_f32 v[86:87], v[38:39], v[174:175], v[234:235] op_sel_hi:[1,0,1]
	ds_write_b64 v1, v[160:161] offset:55552
	s_waitcnt lgkmcnt(9)
	v_pk_mul_f32 v[164:165], v[72:73], v[176:177]
	v_pk_mul_f32 v[166:167], v[80:81], v[176:177]
	ds_read_b128 v[208:211], v2 offset:18432
	v_pk_mul_f32 v[168:169], v[72:73], v[48:49]
	v_pk_mul_f32 v[170:171], v[80:81], v[48:49]
	ds_read_b128 v[212:215], v2 offset:18448
	v_pk_fma_f32 v[164:165], v[74:75], v[178:179], v[164:165]
	v_pk_fma_f32 v[166:167], v[82:83], v[178:179], v[166:167]
	ds_read_b128 v[4:7], v2 offset:6400
	v_pk_fma_f32 v[168:169], v[74:75], v[50:51], v[168:169]
	v_pk_fma_f32 v[170:171], v[82:83], v[50:51], v[170:171]
	ds_read_b128 v[8:11], v2 offset:6416
	s_waitcnt lgkmcnt(12)
	v_pk_fma_f32 v[164:165], v[76:77], v[180:181], v[164:165]
	v_pk_fma_f32 v[166:167], v[84:85], v[180:181], v[166:167]
	ds_read_b128 v[40:43], v2 offset:14592
	v_pk_fma_f32 v[168:169], v[76:77], v[52:53], v[168:169]
	v_pk_fma_f32 v[170:171], v[84:85], v[52:53], v[170:171]
	ds_read_b128 v[44:47], v2 offset:14608
	v_pk_fma_f32 v[164:165], v[78:79], v[182:183], v[164:165]
	v_pk_fma_f32 v[166:167], v[86:87], v[182:183], v[166:167]
	ds_read_b64 v[26:27], v3 offset:43264
	v_pk_fma_f32 v[168:169], v[78:79], v[54:55], v[168:169]
	v_pk_fma_f32 v[170:171], v[86:87], v[54:55], v[170:171]
	ds_read_b128 v[12:15], v2 offset:2304
	s_waitcnt lgkmcnt(13)
	v_pk_mul_f32 v[218:219], v[216:217], v[200:201] op_sel_hi:[0,1]
	v_pk_mul_f32 v[226:227], v[216:217], v[200:201] op_sel:[1,0]
	ds_read_b128 v[28:31], v2 offset:2320
	v_pk_mul_f32 v[220:221], v[216:217], v[202:203] op_sel_hi:[0,1]
	v_pk_mul_f32 v[228:229], v[216:217], v[202:203] op_sel:[1,0]
	ds_read_b128 v[32:35], v2 offset:10496
	v_pk_mul_f32 v[222:223], v[216:217], v[204:205] op_sel_hi:[0,1]
	v_pk_mul_f32 v[230:231], v[216:217], v[204:205] op_sel:[1,0]
	ds_read_b128 v[36:39], v2 offset:10512
	v_pk_mul_f32 v[224:225], v[216:217], v[206:207] op_sel_hi:[0,1]
	v_pk_mul_f32 v[234:235], v[216:217], v[206:207] op_sel:[1,0]
	v_add_f32_e32 v172, v164, v165
	v_add_f32_e32 v174, v166, v167
	v_add_f32_e32 v160, v168, v169
	v_add_f32_e32 v161, v170, v171
	s_waitcnt lgkmcnt(15)
	v_pk_fma_f32 v[218:219], v[72:73], v[184:185], v[218:219]
	v_pk_fma_f32 v[226:227], v[80:81], v[184:185], v[226:227]
	v_pk_fma_f32 v[220:221], v[74:75], v[186:187], v[220:221]
	v_pk_fma_f32 v[228:229], v[82:83], v[186:187], v[228:229]
	v_add_f32_dpp v172, v172, v172 quad_perm:[1,0,3,2] row_mask:0xf bank_mask:0xf bound_ctrl:1
	v_add_f32_dpp v174, v174, v174 quad_perm:[1,0,3,2] row_mask:0xf bank_mask:0xf bound_ctrl:1
	v_add_f32_dpp v160, v160, v160 quad_perm:[1,0,3,2] row_mask:0xf bank_mask:0xf bound_ctrl:1
	v_add_f32_dpp v161, v161, v161 quad_perm:[1,0,3,2] row_mask:0xf bank_mask:0xf bound_ctrl:1
	s_waitcnt lgkmcnt(14)
	v_pk_fma_f32 v[222:223], v[76:77], v[188:189], v[222:223]
	v_pk_fma_f32 v[230:231], v[84:85], v[188:189], v[230:231]
	v_pk_fma_f32 v[224:225], v[78:79], v[190:191], v[224:225]
	v_pk_fma_f32 v[234:235], v[86:87], v[190:191], v[234:235]
	v_add_f32_dpp v172, v172, v172 quad_perm:[2,3,0,1] row_mask:0xf bank_mask:0xf bound_ctrl:1
	v_add_f32_dpp v174, v174, v174 quad_perm:[2,3,0,1] row_mask:0xf bank_mask:0xf bound_ctrl:1
	v_add_f32_dpp v160, v160, v160 quad_perm:[2,3,0,1] row_mask:0xf bank_mask:0xf bound_ctrl:1
	v_add_f32_dpp v161, v161, v161 quad_perm:[2,3,0,1] row_mask:0xf bank_mask:0xf bound_ctrl:1
	v_add_f32_dpp v172, v172, v172 row_half_mirror row_mask:0xf bank_mask:0xf bound_ctrl:1
	v_add_f32_dpp v174, v174, v174 row_half_mirror row_mask:0xf bank_mask:0xf bound_ctrl:1
	v_add_f32_dpp v160, v160, v160 row_half_mirror row_mask:0xf bank_mask:0xf bound_ctrl:1
	v_add_f32_dpp v161, v161, v161 row_half_mirror row_mask:0xf bank_mask:0xf bound_ctrl:1
	s_waitcnt lgkmcnt(13)
	v_pk_fma_f32 v[72:73], v[192:193], v[172:173], v[218:219] op_sel_hi:[1,0,1]
	v_pk_fma_f32 v[80:81], v[192:193], v[174:175], v[226:227] op_sel_hi:[1,0,1]
	v_pk_fma_f32 v[74:75], v[194:195], v[172:173], v[220:221] op_sel_hi:[1,0,1]
	v_pk_fma_f32 v[82:83], v[194:195], v[174:175], v[228:229] op_sel_hi:[1,0,1]
	s_waitcnt lgkmcnt(12)
	v_pk_fma_f32 v[76:77], v[196:197], v[172:173], v[222:223] op_sel_hi:[1,0,1]
	v_pk_fma_f32 v[84:85], v[196:197], v[174:175], v[230:231] op_sel_hi:[1,0,1]
	v_pk_fma_f32 v[78:79], v[198:199], v[172:173], v[224:225] op_sel_hi:[1,0,1]
	v_pk_fma_f32 v[86:87], v[198:199], v[174:175], v[234:235] op_sel_hi:[1,0,1]
	ds_write_b64 v1, v[160:161] offset:55808
	s_waitcnt lgkmcnt(9)
	v_pk_mul_f32 v[164:165], v[72:73], v[4:5]
	v_pk_mul_f32 v[166:167], v[80:81], v[4:5]
	ds_read_b128 v[48:51], v2 offset:18688
	v_pk_mul_f32 v[168:169], v[72:73], v[208:209]
	v_pk_mul_f32 v[170:171], v[80:81], v[208:209]
	ds_read_b128 v[52:55], v2 offset:18704
	v_pk_fma_f32 v[164:165], v[74:75], v[6:7], v[164:165]
	v_pk_fma_f32 v[166:167], v[82:83], v[6:7], v[166:167]
	ds_read_b128 v[176:179], v2 offset:6656
	v_pk_fma_f32 v[168:169], v[74:75], v[210:211], v[168:169]
	v_pk_fma_f32 v[170:171], v[82:83], v[210:211], v[170:171]
	ds_read_b128 v[180:183], v2 offset:6672
	s_waitcnt lgkmcnt(12)
	v_pk_fma_f32 v[164:165], v[76:77], v[8:9], v[164:165]
	v_pk_fma_f32 v[166:167], v[84:85], v[8:9], v[166:167]
	ds_read_b128 v[200:203], v2 offset:14848
	v_pk_fma_f32 v[168:169], v[76:77], v[212:213], v[168:169]
	v_pk_fma_f32 v[170:171], v[84:85], v[212:213], v[170:171]
	ds_read_b128 v[204:207], v2 offset:14864
	v_pk_fma_f32 v[164:165], v[78:79], v[10:11], v[164:165]
	v_pk_fma_f32 v[166:167], v[86:87], v[10:11], v[166:167]
	ds_read_b64 v[216:217], v3 offset:43520
	v_pk_fma_f32 v[168:169], v[78:79], v[214:215], v[168:169]
	v_pk_fma_f32 v[170:171], v[86:87], v[214:215], v[170:171]
	ds_read_b128 v[184:187], v2 offset:2560
	s_waitcnt lgkmcnt(13)
	v_pk_mul_f32 v[218:219], v[26:27], v[40:41] op_sel_hi:[0,1]
	v_pk_mul_f32 v[226:227], v[26:27], v[40:41] op_sel:[1,0]
	ds_read_b128 v[188:191], v2 offset:2576
	v_pk_mul_f32 v[220:221], v[26:27], v[42:43] op_sel_hi:[0,1]
	v_pk_mul_f32 v[228:229], v[26:27], v[42:43] op_sel:[1,0]
	ds_read_b128 v[192:195], v2 offset:10752
	v_pk_mul_f32 v[222:223], v[26:27], v[44:45] op_sel_hi:[0,1]
	v_pk_mul_f32 v[230:231], v[26:27], v[44:45] op_sel:[1,0]
	ds_read_b128 v[196:199], v2 offset:10768
	v_pk_mul_f32 v[224:225], v[26:27], v[46:47] op_sel_hi:[0,1]
	v_pk_mul_f32 v[234:235], v[26:27], v[46:47] op_sel:[1,0]
	v_add_f32_e32 v172, v164, v165
	v_add_f32_e32 v174, v166, v167
	v_add_f32_e32 v160, v168, v169
	v_add_f32_e32 v161, v170, v171
	s_waitcnt lgkmcnt(15)
	v_pk_fma_f32 v[218:219], v[72:73], v[12:13], v[218:219]
	v_pk_fma_f32 v[226:227], v[80:81], v[12:13], v[226:227]
	v_pk_fma_f32 v[220:221], v[74:75], v[14:15], v[220:221]
	v_pk_fma_f32 v[228:229], v[82:83], v[14:15], v[228:229]
	v_add_f32_dpp v172, v172, v172 quad_perm:[1,0,3,2] row_mask:0xf bank_mask:0xf bound_ctrl:1
	v_add_f32_dpp v174, v174, v174 quad_perm:[1,0,3,2] row_mask:0xf bank_mask:0xf bound_ctrl:1
	v_add_f32_dpp v160, v160, v160 quad_perm:[1,0,3,2] row_mask:0xf bank_mask:0xf bound_ctrl:1
	v_add_f32_dpp v161, v161, v161 quad_perm:[1,0,3,2] row_mask:0xf bank_mask:0xf bound_ctrl:1
	s_waitcnt lgkmcnt(14)
	v_pk_fma_f32 v[222:223], v[76:77], v[28:29], v[222:223]
	v_pk_fma_f32 v[230:231], v[84:85], v[28:29], v[230:231]
	v_pk_fma_f32 v[224:225], v[78:79], v[30:31], v[224:225]
	v_pk_fma_f32 v[234:235], v[86:87], v[30:31], v[234:235]
	v_add_f32_dpp v172, v172, v172 quad_perm:[2,3,0,1] row_mask:0xf bank_mask:0xf bound_ctrl:1
	v_add_f32_dpp v174, v174, v174 quad_perm:[2,3,0,1] row_mask:0xf bank_mask:0xf bound_ctrl:1
	v_add_f32_dpp v160, v160, v160 quad_perm:[2,3,0,1] row_mask:0xf bank_mask:0xf bound_ctrl:1
	v_add_f32_dpp v161, v161, v161 quad_perm:[2,3,0,1] row_mask:0xf bank_mask:0xf bound_ctrl:1
	v_add_f32_dpp v172, v172, v172 row_half_mirror row_mask:0xf bank_mask:0xf bound_ctrl:1
	v_add_f32_dpp v174, v174, v174 row_half_mirror row_mask:0xf bank_mask:0xf bound_ctrl:1
	v_add_f32_dpp v160, v160, v160 row_half_mirror row_mask:0xf bank_mask:0xf bound_ctrl:1
	v_add_f32_dpp v161, v161, v161 row_half_mirror row_mask:0xf bank_mask:0xf bound_ctrl:1
	s_waitcnt lgkmcnt(13)
	v_pk_fma_f32 v[72:73], v[32:33], v[172:173], v[218:219] op_sel_hi:[1,0,1]
	v_pk_fma_f32 v[80:81], v[32:33], v[174:175], v[226:227] op_sel_hi:[1,0,1]
	v_pk_fma_f32 v[74:75], v[34:35], v[172:173], v[220:221] op_sel_hi:[1,0,1]
	v_pk_fma_f32 v[82:83], v[34:35], v[174:175], v[228:229] op_sel_hi:[1,0,1]
	s_waitcnt lgkmcnt(12)
	v_pk_fma_f32 v[76:77], v[36:37], v[172:173], v[222:223] op_sel_hi:[1,0,1]
	v_pk_fma_f32 v[84:85], v[36:37], v[174:175], v[230:231] op_sel_hi:[1,0,1]
	v_pk_fma_f32 v[78:79], v[38:39], v[172:173], v[224:225] op_sel_hi:[1,0,1]
	v_pk_fma_f32 v[86:87], v[38:39], v[174:175], v[234:235] op_sel_hi:[1,0,1]
	ds_write_b64 v1, v[160:161] offset:56064
	s_waitcnt lgkmcnt(9)
	v_pk_mul_f32 v[164:165], v[72:73], v[176:177]
	v_pk_mul_f32 v[166:167], v[80:81], v[176:177]
	ds_read_b128 v[208:211], v2 offset:18944
	v_pk_mul_f32 v[168:169], v[72:73], v[48:49]
	v_pk_mul_f32 v[170:171], v[80:81], v[48:49]
	ds_read_b128 v[212:215], v2 offset:18960
	v_pk_fma_f32 v[164:165], v[74:75], v[178:179], v[164:165]
	v_pk_fma_f32 v[166:167], v[82:83], v[178:179], v[166:167]
	ds_read_b128 v[4:7], v2 offset:6912
	v_pk_fma_f32 v[168:169], v[74:75], v[50:51], v[168:169]
	v_pk_fma_f32 v[170:171], v[82:83], v[50:51], v[170:171]
	ds_read_b128 v[8:11], v2 offset:6928
	s_waitcnt lgkmcnt(12)
	v_pk_fma_f32 v[164:165], v[76:77], v[180:181], v[164:165]
	v_pk_fma_f32 v[166:167], v[84:85], v[180:181], v[166:167]
	ds_read_b128 v[40:43], v2 offset:15104
	v_pk_fma_f32 v[168:169], v[76:77], v[52:53], v[168:169]
	v_pk_fma_f32 v[170:171], v[84:85], v[52:53], v[170:171]
	ds_read_b128 v[44:47], v2 offset:15120
	v_pk_fma_f32 v[164:165], v[78:79], v[182:183], v[164:165]
	v_pk_fma_f32 v[166:167], v[86:87], v[182:183], v[166:167]
	ds_read_b64 v[26:27], v3 offset:43776
	v_pk_fma_f32 v[168:169], v[78:79], v[54:55], v[168:169]
	v_pk_fma_f32 v[170:171], v[86:87], v[54:55], v[170:171]
	ds_read_b128 v[12:15], v2 offset:2816
	s_waitcnt lgkmcnt(13)
	v_pk_mul_f32 v[218:219], v[216:217], v[200:201] op_sel_hi:[0,1]
	v_pk_mul_f32 v[226:227], v[216:217], v[200:201] op_sel:[1,0]
	ds_read_b128 v[28:31], v2 offset:2832
	v_pk_mul_f32 v[220:221], v[216:217], v[202:203] op_sel_hi:[0,1]
	v_pk_mul_f32 v[228:229], v[216:217], v[202:203] op_sel:[1,0]
	ds_read_b128 v[32:35], v2 offset:11008
	v_pk_mul_f32 v[222:223], v[216:217], v[204:205] op_sel_hi:[0,1]
	v_pk_mul_f32 v[230:231], v[216:217], v[204:205] op_sel:[1,0]
	ds_read_b128 v[36:39], v2 offset:11024
	v_pk_mul_f32 v[224:225], v[216:217], v[206:207] op_sel_hi:[0,1]
	v_pk_mul_f32 v[234:235], v[216:217], v[206:207] op_sel:[1,0]
	v_add_f32_e32 v172, v164, v165
	v_add_f32_e32 v174, v166, v167
	v_add_f32_e32 v160, v168, v169
	v_add_f32_e32 v161, v170, v171
	s_waitcnt lgkmcnt(15)
	v_pk_fma_f32 v[218:219], v[72:73], v[184:185], v[218:219]
	v_pk_fma_f32 v[226:227], v[80:81], v[184:185], v[226:227]
	v_pk_fma_f32 v[220:221], v[74:75], v[186:187], v[220:221]
	v_pk_fma_f32 v[228:229], v[82:83], v[186:187], v[228:229]
	v_add_f32_dpp v172, v172, v172 quad_perm:[1,0,3,2] row_mask:0xf bank_mask:0xf bound_ctrl:1
	v_add_f32_dpp v174, v174, v174 quad_perm:[1,0,3,2] row_mask:0xf bank_mask:0xf bound_ctrl:1
	v_add_f32_dpp v160, v160, v160 quad_perm:[1,0,3,2] row_mask:0xf bank_mask:0xf bound_ctrl:1
	v_add_f32_dpp v161, v161, v161 quad_perm:[1,0,3,2] row_mask:0xf bank_mask:0xf bound_ctrl:1
	s_waitcnt lgkmcnt(14)
	v_pk_fma_f32 v[222:223], v[76:77], v[188:189], v[222:223]
	v_pk_fma_f32 v[230:231], v[84:85], v[188:189], v[230:231]
	v_pk_fma_f32 v[224:225], v[78:79], v[190:191], v[224:225]
	v_pk_fma_f32 v[234:235], v[86:87], v[190:191], v[234:235]
	v_add_f32_dpp v172, v172, v172 quad_perm:[2,3,0,1] row_mask:0xf bank_mask:0xf bound_ctrl:1
	v_add_f32_dpp v174, v174, v174 quad_perm:[2,3,0,1] row_mask:0xf bank_mask:0xf bound_ctrl:1
	v_add_f32_dpp v160, v160, v160 quad_perm:[2,3,0,1] row_mask:0xf bank_mask:0xf bound_ctrl:1
	v_add_f32_dpp v161, v161, v161 quad_perm:[2,3,0,1] row_mask:0xf bank_mask:0xf bound_ctrl:1
	v_add_f32_dpp v172, v172, v172 row_half_mirror row_mask:0xf bank_mask:0xf bound_ctrl:1
	v_add_f32_dpp v174, v174, v174 row_half_mirror row_mask:0xf bank_mask:0xf bound_ctrl:1
	v_add_f32_dpp v160, v160, v160 row_half_mirror row_mask:0xf bank_mask:0xf bound_ctrl:1
	v_add_f32_dpp v161, v161, v161 row_half_mirror row_mask:0xf bank_mask:0xf bound_ctrl:1
	s_waitcnt lgkmcnt(13)
	v_pk_fma_f32 v[72:73], v[192:193], v[172:173], v[218:219] op_sel_hi:[1,0,1]
	v_pk_fma_f32 v[80:81], v[192:193], v[174:175], v[226:227] op_sel_hi:[1,0,1]
	v_pk_fma_f32 v[74:75], v[194:195], v[172:173], v[220:221] op_sel_hi:[1,0,1]
	v_pk_fma_f32 v[82:83], v[194:195], v[174:175], v[228:229] op_sel_hi:[1,0,1]
	s_waitcnt lgkmcnt(12)
	v_pk_fma_f32 v[76:77], v[196:197], v[172:173], v[222:223] op_sel_hi:[1,0,1]
	v_pk_fma_f32 v[84:85], v[196:197], v[174:175], v[230:231] op_sel_hi:[1,0,1]
	v_pk_fma_f32 v[78:79], v[198:199], v[172:173], v[224:225] op_sel_hi:[1,0,1]
	v_pk_fma_f32 v[86:87], v[198:199], v[174:175], v[234:235] op_sel_hi:[1,0,1]
	ds_write_b64 v1, v[160:161] offset:56320
	s_waitcnt lgkmcnt(9)
	v_pk_mul_f32 v[164:165], v[72:73], v[4:5]
	v_pk_mul_f32 v[166:167], v[80:81], v[4:5]
	ds_read_b128 v[48:51], v2 offset:19200
	v_pk_mul_f32 v[168:169], v[72:73], v[208:209]
	v_pk_mul_f32 v[170:171], v[80:81], v[208:209]
	ds_read_b128 v[52:55], v2 offset:19216
	v_pk_fma_f32 v[164:165], v[74:75], v[6:7], v[164:165]
	v_pk_fma_f32 v[166:167], v[82:83], v[6:7], v[166:167]
	ds_read_b128 v[176:179], v2 offset:7168
	v_pk_fma_f32 v[168:169], v[74:75], v[210:211], v[168:169]
	v_pk_fma_f32 v[170:171], v[82:83], v[210:211], v[170:171]
	ds_read_b128 v[180:183], v2 offset:7184
	s_waitcnt lgkmcnt(12)
	v_pk_fma_f32 v[164:165], v[76:77], v[8:9], v[164:165]
	v_pk_fma_f32 v[166:167], v[84:85], v[8:9], v[166:167]
	ds_read_b128 v[200:203], v2 offset:15360
	v_pk_fma_f32 v[168:169], v[76:77], v[212:213], v[168:169]
	v_pk_fma_f32 v[170:171], v[84:85], v[212:213], v[170:171]
	ds_read_b128 v[204:207], v2 offset:15376
	v_pk_fma_f32 v[164:165], v[78:79], v[10:11], v[164:165]
	v_pk_fma_f32 v[166:167], v[86:87], v[10:11], v[166:167]
	ds_read_b64 v[216:217], v3 offset:44032
	v_pk_fma_f32 v[168:169], v[78:79], v[214:215], v[168:169]
	v_pk_fma_f32 v[170:171], v[86:87], v[214:215], v[170:171]
	ds_read_b128 v[184:187], v2 offset:3072
	s_waitcnt lgkmcnt(13)
	v_pk_mul_f32 v[218:219], v[26:27], v[40:41] op_sel_hi:[0,1]
	v_pk_mul_f32 v[226:227], v[26:27], v[40:41] op_sel:[1,0]
	ds_read_b128 v[188:191], v2 offset:3088
	v_pk_mul_f32 v[220:221], v[26:27], v[42:43] op_sel_hi:[0,1]
	v_pk_mul_f32 v[228:229], v[26:27], v[42:43] op_sel:[1,0]
	ds_read_b128 v[192:195], v2 offset:11264
	v_pk_mul_f32 v[222:223], v[26:27], v[44:45] op_sel_hi:[0,1]
	v_pk_mul_f32 v[230:231], v[26:27], v[44:45] op_sel:[1,0]
	ds_read_b128 v[196:199], v2 offset:11280
	v_pk_mul_f32 v[224:225], v[26:27], v[46:47] op_sel_hi:[0,1]
	v_pk_mul_f32 v[234:235], v[26:27], v[46:47] op_sel:[1,0]
	v_add_f32_e32 v172, v164, v165
	v_add_f32_e32 v174, v166, v167
	v_add_f32_e32 v160, v168, v169
	v_add_f32_e32 v161, v170, v171
	s_waitcnt lgkmcnt(15)
	v_pk_fma_f32 v[218:219], v[72:73], v[12:13], v[218:219]
	v_pk_fma_f32 v[226:227], v[80:81], v[12:13], v[226:227]
	v_pk_fma_f32 v[220:221], v[74:75], v[14:15], v[220:221]
	v_pk_fma_f32 v[228:229], v[82:83], v[14:15], v[228:229]
	v_add_f32_dpp v172, v172, v172 quad_perm:[1,0,3,2] row_mask:0xf bank_mask:0xf bound_ctrl:1
	v_add_f32_dpp v174, v174, v174 quad_perm:[1,0,3,2] row_mask:0xf bank_mask:0xf bound_ctrl:1
	v_add_f32_dpp v160, v160, v160 quad_perm:[1,0,3,2] row_mask:0xf bank_mask:0xf bound_ctrl:1
	v_add_f32_dpp v161, v161, v161 quad_perm:[1,0,3,2] row_mask:0xf bank_mask:0xf bound_ctrl:1
	s_waitcnt lgkmcnt(14)
	v_pk_fma_f32 v[222:223], v[76:77], v[28:29], v[222:223]
	v_pk_fma_f32 v[230:231], v[84:85], v[28:29], v[230:231]
	v_pk_fma_f32 v[224:225], v[78:79], v[30:31], v[224:225]
	v_pk_fma_f32 v[234:235], v[86:87], v[30:31], v[234:235]
	v_add_f32_dpp v172, v172, v172 quad_perm:[2,3,0,1] row_mask:0xf bank_mask:0xf bound_ctrl:1
	v_add_f32_dpp v174, v174, v174 quad_perm:[2,3,0,1] row_mask:0xf bank_mask:0xf bound_ctrl:1
	v_add_f32_dpp v160, v160, v160 quad_perm:[2,3,0,1] row_mask:0xf bank_mask:0xf bound_ctrl:1
	v_add_f32_dpp v161, v161, v161 quad_perm:[2,3,0,1] row_mask:0xf bank_mask:0xf bound_ctrl:1
	v_add_f32_dpp v172, v172, v172 row_half_mirror row_mask:0xf bank_mask:0xf bound_ctrl:1
	v_add_f32_dpp v174, v174, v174 row_half_mirror row_mask:0xf bank_mask:0xf bound_ctrl:1
	v_add_f32_dpp v160, v160, v160 row_half_mirror row_mask:0xf bank_mask:0xf bound_ctrl:1
	v_add_f32_dpp v161, v161, v161 row_half_mirror row_mask:0xf bank_mask:0xf bound_ctrl:1
	s_waitcnt lgkmcnt(13)
	v_pk_fma_f32 v[72:73], v[32:33], v[172:173], v[218:219] op_sel_hi:[1,0,1]
	v_pk_fma_f32 v[80:81], v[32:33], v[174:175], v[226:227] op_sel_hi:[1,0,1]
	v_pk_fma_f32 v[74:75], v[34:35], v[172:173], v[220:221] op_sel_hi:[1,0,1]
	v_pk_fma_f32 v[82:83], v[34:35], v[174:175], v[228:229] op_sel_hi:[1,0,1]
	s_waitcnt lgkmcnt(12)
	v_pk_fma_f32 v[76:77], v[36:37], v[172:173], v[222:223] op_sel_hi:[1,0,1]
	v_pk_fma_f32 v[84:85], v[36:37], v[174:175], v[230:231] op_sel_hi:[1,0,1]
	v_pk_fma_f32 v[78:79], v[38:39], v[172:173], v[224:225] op_sel_hi:[1,0,1]
	v_pk_fma_f32 v[86:87], v[38:39], v[174:175], v[234:235] op_sel_hi:[1,0,1]
	ds_write_b64 v1, v[160:161] offset:56576
	s_waitcnt lgkmcnt(9)
	v_pk_mul_f32 v[164:165], v[72:73], v[176:177]
	v_pk_mul_f32 v[166:167], v[80:81], v[176:177]
	ds_read_b128 v[208:211], v2 offset:19456
	v_pk_mul_f32 v[168:169], v[72:73], v[48:49]
	v_pk_mul_f32 v[170:171], v[80:81], v[48:49]
	ds_read_b128 v[212:215], v2 offset:19472
	v_pk_fma_f32 v[164:165], v[74:75], v[178:179], v[164:165]
	v_pk_fma_f32 v[166:167], v[82:83], v[178:179], v[166:167]
	ds_read_b128 v[4:7], v2 offset:7424
	v_pk_fma_f32 v[168:169], v[74:75], v[50:51], v[168:169]
	v_pk_fma_f32 v[170:171], v[82:83], v[50:51], v[170:171]
	ds_read_b128 v[8:11], v2 offset:7440
	s_waitcnt lgkmcnt(12)
	v_pk_fma_f32 v[164:165], v[76:77], v[180:181], v[164:165]
	v_pk_fma_f32 v[166:167], v[84:85], v[180:181], v[166:167]
	ds_read_b128 v[40:43], v2 offset:15616
	v_pk_fma_f32 v[168:169], v[76:77], v[52:53], v[168:169]
	v_pk_fma_f32 v[170:171], v[84:85], v[52:53], v[170:171]
	ds_read_b128 v[44:47], v2 offset:15632
	v_pk_fma_f32 v[164:165], v[78:79], v[182:183], v[164:165]
	v_pk_fma_f32 v[166:167], v[86:87], v[182:183], v[166:167]
	ds_read_b64 v[26:27], v3 offset:44288
	v_pk_fma_f32 v[168:169], v[78:79], v[54:55], v[168:169]
	v_pk_fma_f32 v[170:171], v[86:87], v[54:55], v[170:171]
	ds_read_b128 v[12:15], v2 offset:3328
	s_waitcnt lgkmcnt(13)
	v_pk_mul_f32 v[218:219], v[216:217], v[200:201] op_sel_hi:[0,1]
	v_pk_mul_f32 v[226:227], v[216:217], v[200:201] op_sel:[1,0]
	ds_read_b128 v[28:31], v2 offset:3344
	v_pk_mul_f32 v[220:221], v[216:217], v[202:203] op_sel_hi:[0,1]
	v_pk_mul_f32 v[228:229], v[216:217], v[202:203] op_sel:[1,0]
	ds_read_b128 v[32:35], v2 offset:11520
	v_pk_mul_f32 v[222:223], v[216:217], v[204:205] op_sel_hi:[0,1]
	v_pk_mul_f32 v[230:231], v[216:217], v[204:205] op_sel:[1,0]
	ds_read_b128 v[36:39], v2 offset:11536
	v_pk_mul_f32 v[224:225], v[216:217], v[206:207] op_sel_hi:[0,1]
	v_pk_mul_f32 v[234:235], v[216:217], v[206:207] op_sel:[1,0]
	v_add_f32_e32 v172, v164, v165
	v_add_f32_e32 v174, v166, v167
	v_add_f32_e32 v160, v168, v169
	v_add_f32_e32 v161, v170, v171
	s_waitcnt lgkmcnt(15)
	v_pk_fma_f32 v[218:219], v[72:73], v[184:185], v[218:219]
	v_pk_fma_f32 v[226:227], v[80:81], v[184:185], v[226:227]
	v_pk_fma_f32 v[220:221], v[74:75], v[186:187], v[220:221]
	v_pk_fma_f32 v[228:229], v[82:83], v[186:187], v[228:229]
	v_add_f32_dpp v172, v172, v172 quad_perm:[1,0,3,2] row_mask:0xf bank_mask:0xf bound_ctrl:1
	v_add_f32_dpp v174, v174, v174 quad_perm:[1,0,3,2] row_mask:0xf bank_mask:0xf bound_ctrl:1
	v_add_f32_dpp v160, v160, v160 quad_perm:[1,0,3,2] row_mask:0xf bank_mask:0xf bound_ctrl:1
	v_add_f32_dpp v161, v161, v161 quad_perm:[1,0,3,2] row_mask:0xf bank_mask:0xf bound_ctrl:1
	s_waitcnt lgkmcnt(14)
	v_pk_fma_f32 v[222:223], v[76:77], v[188:189], v[222:223]
	v_pk_fma_f32 v[230:231], v[84:85], v[188:189], v[230:231]
	v_pk_fma_f32 v[224:225], v[78:79], v[190:191], v[224:225]
	v_pk_fma_f32 v[234:235], v[86:87], v[190:191], v[234:235]
	v_add_f32_dpp v172, v172, v172 quad_perm:[2,3,0,1] row_mask:0xf bank_mask:0xf bound_ctrl:1
	v_add_f32_dpp v174, v174, v174 quad_perm:[2,3,0,1] row_mask:0xf bank_mask:0xf bound_ctrl:1
	v_add_f32_dpp v160, v160, v160 quad_perm:[2,3,0,1] row_mask:0xf bank_mask:0xf bound_ctrl:1
	v_add_f32_dpp v161, v161, v161 quad_perm:[2,3,0,1] row_mask:0xf bank_mask:0xf bound_ctrl:1
	v_add_f32_dpp v172, v172, v172 row_half_mirror row_mask:0xf bank_mask:0xf bound_ctrl:1
	v_add_f32_dpp v174, v174, v174 row_half_mirror row_mask:0xf bank_mask:0xf bound_ctrl:1
	v_add_f32_dpp v160, v160, v160 row_half_mirror row_mask:0xf bank_mask:0xf bound_ctrl:1
	v_add_f32_dpp v161, v161, v161 row_half_mirror row_mask:0xf bank_mask:0xf bound_ctrl:1
	s_waitcnt lgkmcnt(13)
	v_pk_fma_f32 v[72:73], v[192:193], v[172:173], v[218:219] op_sel_hi:[1,0,1]
	v_pk_fma_f32 v[80:81], v[192:193], v[174:175], v[226:227] op_sel_hi:[1,0,1]
	v_pk_fma_f32 v[74:75], v[194:195], v[172:173], v[220:221] op_sel_hi:[1,0,1]
	v_pk_fma_f32 v[82:83], v[194:195], v[174:175], v[228:229] op_sel_hi:[1,0,1]
	s_waitcnt lgkmcnt(12)
	v_pk_fma_f32 v[76:77], v[196:197], v[172:173], v[222:223] op_sel_hi:[1,0,1]
	v_pk_fma_f32 v[84:85], v[196:197], v[174:175], v[230:231] op_sel_hi:[1,0,1]
	v_pk_fma_f32 v[78:79], v[198:199], v[172:173], v[224:225] op_sel_hi:[1,0,1]
	v_pk_fma_f32 v[86:87], v[198:199], v[174:175], v[234:235] op_sel_hi:[1,0,1]
	ds_write_b64 v1, v[160:161] offset:56832
	s_waitcnt lgkmcnt(9)
	v_pk_mul_f32 v[164:165], v[72:73], v[4:5]
	v_pk_mul_f32 v[166:167], v[80:81], v[4:5]
	ds_read_b128 v[48:51], v2 offset:19712
	v_pk_mul_f32 v[168:169], v[72:73], v[208:209]
	v_pk_mul_f32 v[170:171], v[80:81], v[208:209]
	ds_read_b128 v[52:55], v2 offset:19728
	v_pk_fma_f32 v[164:165], v[74:75], v[6:7], v[164:165]
	v_pk_fma_f32 v[166:167], v[82:83], v[6:7], v[166:167]
	ds_read_b128 v[176:179], v2 offset:7680
	v_pk_fma_f32 v[168:169], v[74:75], v[210:211], v[168:169]
	v_pk_fma_f32 v[170:171], v[82:83], v[210:211], v[170:171]
	ds_read_b128 v[180:183], v2 offset:7696
	s_waitcnt lgkmcnt(12)
	v_pk_fma_f32 v[164:165], v[76:77], v[8:9], v[164:165]
	v_pk_fma_f32 v[166:167], v[84:85], v[8:9], v[166:167]
	ds_read_b128 v[200:203], v2 offset:15872
	v_pk_fma_f32 v[168:169], v[76:77], v[212:213], v[168:169]
	v_pk_fma_f32 v[170:171], v[84:85], v[212:213], v[170:171]
	ds_read_b128 v[204:207], v2 offset:15888
	v_pk_fma_f32 v[164:165], v[78:79], v[10:11], v[164:165]
	v_pk_fma_f32 v[166:167], v[86:87], v[10:11], v[166:167]
	ds_read_b64 v[216:217], v3 offset:44544
	v_pk_fma_f32 v[168:169], v[78:79], v[214:215], v[168:169]
	v_pk_fma_f32 v[170:171], v[86:87], v[214:215], v[170:171]
	ds_read_b128 v[184:187], v2 offset:3584
	s_waitcnt lgkmcnt(13)
	v_pk_mul_f32 v[218:219], v[26:27], v[40:41] op_sel_hi:[0,1]
	v_pk_mul_f32 v[226:227], v[26:27], v[40:41] op_sel:[1,0]
	ds_read_b128 v[188:191], v2 offset:3600
	v_pk_mul_f32 v[220:221], v[26:27], v[42:43] op_sel_hi:[0,1]
	v_pk_mul_f32 v[228:229], v[26:27], v[42:43] op_sel:[1,0]
	ds_read_b128 v[192:195], v2 offset:11776
	v_pk_mul_f32 v[222:223], v[26:27], v[44:45] op_sel_hi:[0,1]
	v_pk_mul_f32 v[230:231], v[26:27], v[44:45] op_sel:[1,0]
	ds_read_b128 v[196:199], v2 offset:11792
	v_pk_mul_f32 v[224:225], v[26:27], v[46:47] op_sel_hi:[0,1]
	v_pk_mul_f32 v[234:235], v[26:27], v[46:47] op_sel:[1,0]
	v_add_f32_e32 v172, v164, v165
	v_add_f32_e32 v174, v166, v167
	v_add_f32_e32 v160, v168, v169
	v_add_f32_e32 v161, v170, v171
	s_waitcnt lgkmcnt(15)
	v_pk_fma_f32 v[218:219], v[72:73], v[12:13], v[218:219]
	v_pk_fma_f32 v[226:227], v[80:81], v[12:13], v[226:227]
	v_pk_fma_f32 v[220:221], v[74:75], v[14:15], v[220:221]
	v_pk_fma_f32 v[228:229], v[82:83], v[14:15], v[228:229]
	v_add_f32_dpp v172, v172, v172 quad_perm:[1,0,3,2] row_mask:0xf bank_mask:0xf bound_ctrl:1
	v_add_f32_dpp v174, v174, v174 quad_perm:[1,0,3,2] row_mask:0xf bank_mask:0xf bound_ctrl:1
	v_add_f32_dpp v160, v160, v160 quad_perm:[1,0,3,2] row_mask:0xf bank_mask:0xf bound_ctrl:1
	v_add_f32_dpp v161, v161, v161 quad_perm:[1,0,3,2] row_mask:0xf bank_mask:0xf bound_ctrl:1
	s_waitcnt lgkmcnt(14)
	v_pk_fma_f32 v[222:223], v[76:77], v[28:29], v[222:223]
	v_pk_fma_f32 v[230:231], v[84:85], v[28:29], v[230:231]
	v_pk_fma_f32 v[224:225], v[78:79], v[30:31], v[224:225]
	v_pk_fma_f32 v[234:235], v[86:87], v[30:31], v[234:235]
	v_add_f32_dpp v172, v172, v172 quad_perm:[2,3,0,1] row_mask:0xf bank_mask:0xf bound_ctrl:1
	v_add_f32_dpp v174, v174, v174 quad_perm:[2,3,0,1] row_mask:0xf bank_mask:0xf bound_ctrl:1
	v_add_f32_dpp v160, v160, v160 quad_perm:[2,3,0,1] row_mask:0xf bank_mask:0xf bound_ctrl:1
	v_add_f32_dpp v161, v161, v161 quad_perm:[2,3,0,1] row_mask:0xf bank_mask:0xf bound_ctrl:1
	v_add_f32_dpp v172, v172, v172 row_half_mirror row_mask:0xf bank_mask:0xf bound_ctrl:1
	v_add_f32_dpp v174, v174, v174 row_half_mirror row_mask:0xf bank_mask:0xf bound_ctrl:1
	v_add_f32_dpp v160, v160, v160 row_half_mirror row_mask:0xf bank_mask:0xf bound_ctrl:1
	v_add_f32_dpp v161, v161, v161 row_half_mirror row_mask:0xf bank_mask:0xf bound_ctrl:1
	s_waitcnt lgkmcnt(13)
	v_pk_fma_f32 v[72:73], v[32:33], v[172:173], v[218:219] op_sel_hi:[1,0,1]
	v_pk_fma_f32 v[80:81], v[32:33], v[174:175], v[226:227] op_sel_hi:[1,0,1]
	v_pk_fma_f32 v[74:75], v[34:35], v[172:173], v[220:221] op_sel_hi:[1,0,1]
	v_pk_fma_f32 v[82:83], v[34:35], v[174:175], v[228:229] op_sel_hi:[1,0,1]
	s_waitcnt lgkmcnt(12)
	v_pk_fma_f32 v[76:77], v[36:37], v[172:173], v[222:223] op_sel_hi:[1,0,1]
	v_pk_fma_f32 v[84:85], v[36:37], v[174:175], v[230:231] op_sel_hi:[1,0,1]
	v_pk_fma_f32 v[78:79], v[38:39], v[172:173], v[224:225] op_sel_hi:[1,0,1]
	v_pk_fma_f32 v[86:87], v[38:39], v[174:175], v[234:235] op_sel_hi:[1,0,1]
	ds_write_b64 v1, v[160:161] offset:57088
	s_waitcnt lgkmcnt(9)
	v_pk_mul_f32 v[164:165], v[72:73], v[176:177]
	v_pk_mul_f32 v[166:167], v[80:81], v[176:177]
	ds_read_b128 v[208:211], v2 offset:19968
	v_pk_mul_f32 v[168:169], v[72:73], v[48:49]
	v_pk_mul_f32 v[170:171], v[80:81], v[48:49]
	ds_read_b128 v[212:215], v2 offset:19984
	v_pk_fma_f32 v[164:165], v[74:75], v[178:179], v[164:165]
	v_pk_fma_f32 v[166:167], v[82:83], v[178:179], v[166:167]
	ds_read_b128 v[4:7], v2 offset:7936
	v_pk_fma_f32 v[168:169], v[74:75], v[50:51], v[168:169]
	v_pk_fma_f32 v[170:171], v[82:83], v[50:51], v[170:171]
	ds_read_b128 v[8:11], v2 offset:7952
	s_waitcnt lgkmcnt(12)
	v_pk_fma_f32 v[164:165], v[76:77], v[180:181], v[164:165]
	v_pk_fma_f32 v[166:167], v[84:85], v[180:181], v[166:167]
	ds_read_b128 v[40:43], v2 offset:16128
	v_pk_fma_f32 v[168:169], v[76:77], v[52:53], v[168:169]
	v_pk_fma_f32 v[170:171], v[84:85], v[52:53], v[170:171]
	ds_read_b128 v[44:47], v2 offset:16144
	v_pk_fma_f32 v[164:165], v[78:79], v[182:183], v[164:165]
	v_pk_fma_f32 v[166:167], v[86:87], v[182:183], v[166:167]
	ds_read_b64 v[26:27], v3 offset:44800
	v_pk_fma_f32 v[168:169], v[78:79], v[54:55], v[168:169]
	v_pk_fma_f32 v[170:171], v[86:87], v[54:55], v[170:171]
	ds_read_b128 v[12:15], v2 offset:3840
	s_waitcnt lgkmcnt(13)
	v_pk_mul_f32 v[218:219], v[216:217], v[200:201] op_sel_hi:[0,1]
	v_pk_mul_f32 v[226:227], v[216:217], v[200:201] op_sel:[1,0]
	ds_read_b128 v[28:31], v2 offset:3856
	v_pk_mul_f32 v[220:221], v[216:217], v[202:203] op_sel_hi:[0,1]
	v_pk_mul_f32 v[228:229], v[216:217], v[202:203] op_sel:[1,0]
	ds_read_b128 v[32:35], v2 offset:12032
	v_pk_mul_f32 v[222:223], v[216:217], v[204:205] op_sel_hi:[0,1]
	v_pk_mul_f32 v[230:231], v[216:217], v[204:205] op_sel:[1,0]
	ds_read_b128 v[36:39], v2 offset:12048
	v_pk_mul_f32 v[224:225], v[216:217], v[206:207] op_sel_hi:[0,1]
	v_pk_mul_f32 v[234:235], v[216:217], v[206:207] op_sel:[1,0]
	v_add_f32_e32 v172, v164, v165
	v_add_f32_e32 v174, v166, v167
	v_add_f32_e32 v160, v168, v169
	v_add_f32_e32 v161, v170, v171
	s_waitcnt lgkmcnt(15)
	v_pk_fma_f32 v[218:219], v[72:73], v[184:185], v[218:219]
	v_pk_fma_f32 v[226:227], v[80:81], v[184:185], v[226:227]
	v_pk_fma_f32 v[220:221], v[74:75], v[186:187], v[220:221]
	v_pk_fma_f32 v[228:229], v[82:83], v[186:187], v[228:229]
	v_add_f32_dpp v172, v172, v172 quad_perm:[1,0,3,2] row_mask:0xf bank_mask:0xf bound_ctrl:1
	v_add_f32_dpp v174, v174, v174 quad_perm:[1,0,3,2] row_mask:0xf bank_mask:0xf bound_ctrl:1
	v_add_f32_dpp v160, v160, v160 quad_perm:[1,0,3,2] row_mask:0xf bank_mask:0xf bound_ctrl:1
	v_add_f32_dpp v161, v161, v161 quad_perm:[1,0,3,2] row_mask:0xf bank_mask:0xf bound_ctrl:1
	s_waitcnt lgkmcnt(14)
	v_pk_fma_f32 v[222:223], v[76:77], v[188:189], v[222:223]
	v_pk_fma_f32 v[230:231], v[84:85], v[188:189], v[230:231]
	v_pk_fma_f32 v[224:225], v[78:79], v[190:191], v[224:225]
	v_pk_fma_f32 v[234:235], v[86:87], v[190:191], v[234:235]
	v_add_f32_dpp v172, v172, v172 quad_perm:[2,3,0,1] row_mask:0xf bank_mask:0xf bound_ctrl:1
	v_add_f32_dpp v174, v174, v174 quad_perm:[2,3,0,1] row_mask:0xf bank_mask:0xf bound_ctrl:1
	v_add_f32_dpp v160, v160, v160 quad_perm:[2,3,0,1] row_mask:0xf bank_mask:0xf bound_ctrl:1
	v_add_f32_dpp v161, v161, v161 quad_perm:[2,3,0,1] row_mask:0xf bank_mask:0xf bound_ctrl:1
	v_add_f32_dpp v172, v172, v172 row_half_mirror row_mask:0xf bank_mask:0xf bound_ctrl:1
	v_add_f32_dpp v174, v174, v174 row_half_mirror row_mask:0xf bank_mask:0xf bound_ctrl:1
	v_add_f32_dpp v160, v160, v160 row_half_mirror row_mask:0xf bank_mask:0xf bound_ctrl:1
	v_add_f32_dpp v161, v161, v161 row_half_mirror row_mask:0xf bank_mask:0xf bound_ctrl:1
	s_waitcnt lgkmcnt(13)
	v_pk_fma_f32 v[72:73], v[192:193], v[172:173], v[218:219] op_sel_hi:[1,0,1]
	v_pk_fma_f32 v[80:81], v[192:193], v[174:175], v[226:227] op_sel_hi:[1,0,1]
	v_pk_fma_f32 v[74:75], v[194:195], v[172:173], v[220:221] op_sel_hi:[1,0,1]
	v_pk_fma_f32 v[82:83], v[194:195], v[174:175], v[228:229] op_sel_hi:[1,0,1]
	s_waitcnt lgkmcnt(12)
	v_pk_fma_f32 v[76:77], v[196:197], v[172:173], v[222:223] op_sel_hi:[1,0,1]
	v_pk_fma_f32 v[84:85], v[196:197], v[174:175], v[230:231] op_sel_hi:[1,0,1]
	v_pk_fma_f32 v[78:79], v[198:199], v[172:173], v[224:225] op_sel_hi:[1,0,1]
	v_pk_fma_f32 v[86:87], v[198:199], v[174:175], v[234:235] op_sel_hi:[1,0,1]
	ds_write_b64 v1, v[160:161] offset:57344
	s_waitcnt lgkmcnt(9)
	v_pk_mul_f32 v[164:165], v[72:73], v[4:5]
	v_pk_mul_f32 v[166:167], v[80:81], v[4:5]
	ds_read_b128 v[48:51], v2 offset:20224
	v_pk_mul_f32 v[168:169], v[72:73], v[208:209]
	v_pk_mul_f32 v[170:171], v[80:81], v[208:209]
	ds_read_b128 v[52:55], v2 offset:20240
	v_pk_fma_f32 v[164:165], v[74:75], v[6:7], v[164:165]
	v_pk_fma_f32 v[166:167], v[82:83], v[6:7], v[166:167]
	v_pk_fma_f32 v[168:169], v[74:75], v[210:211], v[168:169]
	v_pk_fma_f32 v[170:171], v[82:83], v[210:211], v[170:171]
	s_waitcnt lgkmcnt(10)
	v_pk_fma_f32 v[164:165], v[76:77], v[8:9], v[164:165]
	v_pk_fma_f32 v[166:167], v[84:85], v[8:9], v[166:167]
	v_pk_fma_f32 v[168:169], v[76:77], v[212:213], v[168:169]
	v_pk_fma_f32 v[170:171], v[84:85], v[212:213], v[170:171]
	v_pk_fma_f32 v[164:165], v[78:79], v[10:11], v[164:165]
	v_pk_fma_f32 v[166:167], v[86:87], v[10:11], v[166:167]
	v_pk_fma_f32 v[168:169], v[78:79], v[214:215], v[168:169]
	v_pk_fma_f32 v[170:171], v[86:87], v[214:215], v[170:171]
	s_waitcnt lgkmcnt(7)
	v_pk_mul_f32 v[218:219], v[26:27], v[40:41] op_sel_hi:[0,1]
	v_pk_mul_f32 v[226:227], v[26:27], v[40:41] op_sel:[1,0]
	v_pk_mul_f32 v[220:221], v[26:27], v[42:43] op_sel_hi:[0,1]
	v_pk_mul_f32 v[228:229], v[26:27], v[42:43] op_sel:[1,0]
	v_pk_mul_f32 v[222:223], v[26:27], v[44:45] op_sel_hi:[0,1]
	v_pk_mul_f32 v[230:231], v[26:27], v[44:45] op_sel:[1,0]
	v_pk_mul_f32 v[224:225], v[26:27], v[46:47] op_sel_hi:[0,1]
	v_pk_mul_f32 v[234:235], v[26:27], v[46:47] op_sel:[1,0]
	v_add_f32_e32 v172, v164, v165
	v_add_f32_e32 v174, v166, v167
	v_add_f32_e32 v160, v168, v169
	v_add_f32_e32 v161, v170, v171
	s_waitcnt lgkmcnt(6)
	v_pk_fma_f32 v[218:219], v[72:73], v[12:13], v[218:219]
	v_pk_fma_f32 v[226:227], v[80:81], v[12:13], v[226:227]
	v_pk_fma_f32 v[220:221], v[74:75], v[14:15], v[220:221]
	v_pk_fma_f32 v[228:229], v[82:83], v[14:15], v[228:229]
	v_add_f32_dpp v172, v172, v172 quad_perm:[1,0,3,2] row_mask:0xf bank_mask:0xf bound_ctrl:1
	v_add_f32_dpp v174, v174, v174 quad_perm:[1,0,3,2] row_mask:0xf bank_mask:0xf bound_ctrl:1
	v_add_f32_dpp v160, v160, v160 quad_perm:[1,0,3,2] row_mask:0xf bank_mask:0xf bound_ctrl:1
	v_add_f32_dpp v161, v161, v161 quad_perm:[1,0,3,2] row_mask:0xf bank_mask:0xf bound_ctrl:1
	s_waitcnt lgkmcnt(5)
	v_pk_fma_f32 v[222:223], v[76:77], v[28:29], v[222:223]
	v_pk_fma_f32 v[230:231], v[84:85], v[28:29], v[230:231]
	v_pk_fma_f32 v[224:225], v[78:79], v[30:31], v[224:225]
	v_pk_fma_f32 v[234:235], v[86:87], v[30:31], v[234:235]
	v_add_f32_dpp v172, v172, v172 quad_perm:[2,3,0,1] row_mask:0xf bank_mask:0xf bound_ctrl:1
	v_add_f32_dpp v174, v174, v174 quad_perm:[2,3,0,1] row_mask:0xf bank_mask:0xf bound_ctrl:1
	v_add_f32_dpp v160, v160, v160 quad_perm:[2,3,0,1] row_mask:0xf bank_mask:0xf bound_ctrl:1
	v_add_f32_dpp v161, v161, v161 quad_perm:[2,3,0,1] row_mask:0xf bank_mask:0xf bound_ctrl:1
	v_add_f32_dpp v172, v172, v172 row_half_mirror row_mask:0xf bank_mask:0xf bound_ctrl:1
	v_add_f32_dpp v174, v174, v174 row_half_mirror row_mask:0xf bank_mask:0xf bound_ctrl:1
	v_add_f32_dpp v160, v160, v160 row_half_mirror row_mask:0xf bank_mask:0xf bound_ctrl:1
	v_add_f32_dpp v161, v161, v161 row_half_mirror row_mask:0xf bank_mask:0xf bound_ctrl:1
	s_waitcnt lgkmcnt(4)
	v_pk_fma_f32 v[72:73], v[32:33], v[172:173], v[218:219] op_sel_hi:[1,0,1]
	v_pk_fma_f32 v[80:81], v[32:33], v[174:175], v[226:227] op_sel_hi:[1,0,1]
	v_pk_fma_f32 v[74:75], v[34:35], v[172:173], v[220:221] op_sel_hi:[1,0,1]
	v_pk_fma_f32 v[82:83], v[34:35], v[174:175], v[228:229] op_sel_hi:[1,0,1]
	s_waitcnt lgkmcnt(3)
	v_pk_fma_f32 v[76:77], v[36:37], v[172:173], v[222:223] op_sel_hi:[1,0,1]
	v_pk_fma_f32 v[84:85], v[36:37], v[174:175], v[230:231] op_sel_hi:[1,0,1]
	v_pk_fma_f32 v[78:79], v[38:39], v[172:173], v[224:225] op_sel_hi:[1,0,1]
	v_pk_fma_f32 v[86:87], v[38:39], v[174:175], v[234:235] op_sel_hi:[1,0,1]
	ds_write_b64 v1, v[160:161] offset:57600
	s_waitcnt lgkmcnt(2)
	v_pk_mul_f32 v[168:169], v[72:73], v[48:49]
	v_pk_mul_f32 v[170:171], v[80:81], v[48:49]
	v_pk_fma_f32 v[168:169], v[74:75], v[50:51], v[168:169]
	v_pk_fma_f32 v[170:171], v[82:83], v[50:51], v[170:171]
	s_waitcnt lgkmcnt(1)
	v_pk_fma_f32 v[168:169], v[76:77], v[52:53], v[168:169]
	v_pk_fma_f32 v[170:171], v[84:85], v[52:53], v[170:171]
	v_pk_fma_f32 v[168:169], v[78:79], v[54:55], v[168:169]
	v_pk_fma_f32 v[170:171], v[86:87], v[54:55], v[170:171]
	v_add_f32_e32 v160, v168, v169
	v_add_f32_e32 v161, v170, v171
	s_nop 0
	v_add_f32_dpp v160, v160, v160 quad_perm:[1,0,3,2] row_mask:0xf bank_mask:0xf bound_ctrl:1
	v_add_f32_dpp v161, v161, v161 quad_perm:[1,0,3,2] row_mask:0xf bank_mask:0xf bound_ctrl:1
	s_nop 0
	v_add_f32_dpp v160, v160, v160 quad_perm:[2,3,0,1] row_mask:0xf bank_mask:0xf bound_ctrl:1
	v_add_f32_dpp v161, v161, v161 quad_perm:[2,3,0,1] row_mask:0xf bank_mask:0xf bound_ctrl:1
	s_nop 0
	v_add_f32_dpp v160, v160, v160 row_half_mirror row_mask:0xf bank_mask:0xf bound_ctrl:1
	v_add_f32_dpp v161, v161, v161 row_half_mirror row_mask:0xf bank_mask:0xf bound_ctrl:1
	ds_write_b64 v1, v[160:161] offset:57856
	s_setprio 0
	s_add_i32 s3, s2, 1
	s_mov_b64 s[36:37], 0
